# GEMM epilogue stores write-through (sc1)
# speedup vs baseline: 1.0192x; 1.0192x over previous
.LBB0_828:
	s_cmp_eq_u32 s26, s43
	v_lshl_or_b32 v130, s26, 8, v225
	s_cselect_b64 s[26:27], -1, 0
	s_and_b64 s[26:27], s[12:13], s[26:27]
	v_mad_i64_i32 v[136:137], s[28:29], s41, v204, 0
	s_and_b64 s[26:27], s[16:17], s[26:27]
	v_ashrrev_i32_e32 v131, 31, v130
	v_lshl_add_u64 v[136:137], v[136:137], 1, s[14:15]
	s_and_b64 s[26:27], s[26:27], s[0:1]
	v_cvt_pk_bf16_f32 v142, v126, v127
	v_cvt_pk_bf16_f32 v143, v128, v129
	v_cvt_pk_bf16_f32 v144, v122, v123
	v_cvt_pk_bf16_f32 v145, v124, v125
	v_lshl_add_u64 v[136:137], v[130:131], 1, v[136:137]
	global_store_dwordx4 v[136:137], v[142:145], off sc1
	s_and_saveexec_b64 s[28:29], s[26:27]
	s_cbranch_execz .LBB0_830
	v_lshl_add_u64 v[142:143], v[160:161], 0, v[206:207]
	global_store_dwordx4 v[142:143], v[126:129], off sc1
	global_store_dwordx4 v[142:143], v[122:125], off offset:16 sc1

.LBB0_846:
	v_mul_f32_e32 v116, 0x4b800000, v208
	v_cndmask_b32_e64 v116, v208, v116, s[8:9]
	v_rsq_f32_e32 v116, v116
	v_cvt_pk_bf16_f32 v118, v118, v119
	v_cvt_pk_bf16_f32 v119, v120, v121
	v_cvt_pk_bf16_f32 v120, v114, v115
	v_mul_f32_e32 v114, 0x45800000, v116
	v_cndmask_b32_e64 v116, v116, v114, s[8:9]
	v_cvt_pk_bf16_f32 v121, v122, v117
	s_and_b64 vcc, exec, s[6:7]
	v_mul_f32_e32 v110, v110, v116
	global_store_dwordx4 v[136:137], v[118:121], off offset:256 sc1
	s_cbranch_vccnz .LBB0_848
	v_mul_f32_e32 v114, 0x3d372713, v110
	v_mul_f32_e32 v114, v110, v114
	v_fma_f32 v114, v110, v114, v110
	v_mul_f32_e32 v114, 0xbfcc422a, v114
	v_mul_f32_e32 v114, 0x3fb8aa3b, v114
	v_exp_f32_e32 v114, v114
	s_nop 0
	v_add_f32_e32 v114, 1.0, v114
	v_rcp_f32_e32 v114, v114
	s_nop 0
	v_mul_f32_e32 v110, v110, v114

.LBB0_862:
	v_mad_i64_i32 v[114:115], s[8:9], s41, v202, 0
	v_lshl_add_u64 v[114:115], v[114:115], 1, s[14:15]
	v_cvt_pk_bf16_f32 v118, v110, v111
	v_cvt_pk_bf16_f32 v119, v112, v113
	v_cvt_pk_bf16_f32 v120, v106, v107
	v_cvt_pk_bf16_f32 v121, v108, v109
	v_lshl_add_u64 v[114:115], v[130:131], 1, v[114:115]
	global_store_dwordx4 v[114:115], v[118:121], off sc1
	s_and_saveexec_b64 s[8:9], s[26:27]
	s_cbranch_execz .LBB0_864
	v_lshl_add_u64 v[118:119], v[160:161], 0, v[200:201]
	global_store_dwordx4 v[118:119], v[110:113], off sc1
	global_store_dwordx4 v[118:119], v[106:109], off offset:16 sc1

.LBB0_880:
	s_waitcnt lgkmcnt(4)
	v_pk_add_f32 v[98:99], v[146:147], v[148:149]
	s_mov_b32 s8, 0x3a800000
	v_pk_fma_f32 v[98:99], v[98:99], s[8:9], v[240:241] op_sel_hi:[1,0,0]
	v_cvt_pk_bf16_f32 v102, v102, v103
	v_mul_f32_e32 v108, 0x4b800000, v99
	v_cmp_gt_f32_e32 vcc, s91, v99
	v_cmp_gt_f32_e64 s[8:9], s91, v98
	s_nop 0
	v_cndmask_b32_e32 v99, v99, v108, vcc
	v_rsq_f32_e32 v99, v99
	s_nop 0
	v_mul_f32_e32 v103, 0x45800000, v99
	v_cndmask_b32_e32 v99, v99, v103, vcc
	v_cvt_pk_bf16_f32 v103, v104, v105
	v_cvt_pk_bf16_f32 v104, v106, v107
	v_cvt_pk_bf16_f32 v105, v100, v101
	s_and_b64 vcc, exec, s[6:7]
	v_mul_f32_e32 v94, v94, v99
	global_store_dwordx4 v[114:115], v[102:105], off offset:256 sc1
	s_cbranch_vccnz .LBB0_882
	v_mul_f32_e32 v100, 0x3d372713, v94
	v_mul_f32_e32 v100, v94, v100
	v_fma_f32 v100, v94, v100, v94
	v_mul_f32_e32 v100, 0xbfcc422a, v100
	v_mul_f32_e32 v100, 0x3fb8aa3b, v100
	v_exp_f32_e32 v100, v100
	s_nop 0
	v_add_f32_e32 v100, 1.0, v100
	v_rcp_f32_e32 v100, v100
	s_nop 0
	v_mul_f32_e32 v94, v94, v100

.LBB0_896:
	v_mad_i64_i32 v[100:101], s[28:29], s41, v198, 0
	v_lshl_add_u64 v[100:101], v[100:101], 1, s[14:15]
	v_cvt_pk_bf16_f32 v102, v94, v95
	v_cvt_pk_bf16_f32 v103, v96, v97
	v_cvt_pk_bf16_f32 v104, v90, v91
	v_cvt_pk_bf16_f32 v105, v92, v93
	v_lshl_add_u64 v[100:101], v[130:131], 1, v[100:101]
	global_store_dwordx4 v[100:101], v[102:105], off sc1
	s_and_saveexec_b64 s[28:29], s[26:27]
	s_cbranch_execz .LBB0_898
	v_lshl_add_u64 v[102:103], v[160:161], 0, v[196:197]
	global_store_dwordx4 v[102:103], v[94:97], off sc1
	global_store_dwordx4 v[102:103], v[90:93], off offset:16 sc1

.LBB0_914:
	v_mul_f32_e32 v84, 0x4b800000, v98
	v_cndmask_b32_e64 v84, v98, v84, s[8:9]
	v_rsq_f32_e32 v84, v84
	v_cvt_pk_bf16_f32 v86, v86, v87
	v_cvt_pk_bf16_f32 v87, v88, v89
	v_cvt_pk_bf16_f32 v88, v82, v83
	v_mul_f32_e32 v82, 0x45800000, v84
	v_cndmask_b32_e64 v84, v84, v82, s[8:9]
	v_cvt_pk_bf16_f32 v89, v90, v85
	s_and_b64 vcc, exec, s[6:7]
	v_mul_f32_e32 v78, v78, v84
	global_store_dwordx4 v[100:101], v[86:89], off offset:256 sc1
	s_cbranch_vccnz .LBB0_916
	v_mul_f32_e32 v82, 0x3d372713, v78
	v_mul_f32_e32 v82, v78, v82
	v_fma_f32 v82, v78, v82, v78
	v_mul_f32_e32 v82, 0xbfcc422a, v82
	v_mul_f32_e32 v82, 0x3fb8aa3b, v82
	v_exp_f32_e32 v82, v82
	s_nop 0
	v_add_f32_e32 v82, 1.0, v82
	v_rcp_f32_e32 v82, v82
	s_nop 0
	v_mul_f32_e32 v78, v78, v82

.LBB0_930:
	v_mad_i64_i32 v[82:83], s[8:9], s41, v194, 0
	v_lshl_add_u64 v[82:83], v[82:83], 1, s[14:15]
	v_cvt_pk_bf16_f32 v86, v78, v79
	v_cvt_pk_bf16_f32 v87, v80, v81
	v_cvt_pk_bf16_f32 v88, v74, v75
	v_cvt_pk_bf16_f32 v89, v76, v77
	v_lshl_add_u64 v[82:83], v[130:131], 1, v[82:83]
	global_store_dwordx4 v[82:83], v[86:89], off sc1
	s_and_saveexec_b64 s[8:9], s[26:27]
	s_cbranch_execz .LBB0_932
	v_lshl_add_u64 v[86:87], v[160:161], 0, v[192:193]
	global_store_dwordx4 v[86:87], v[78:81], off sc1
	global_store_dwordx4 v[86:87], v[74:77], off offset:16 sc1

.LBB0_948:
	s_waitcnt lgkmcnt(2)
	v_pk_add_f32 v[66:67], v[138:139], v[140:141]
	s_mov_b32 s8, 0x3a800000
	v_pk_fma_f32 v[66:67], v[66:67], s[8:9], v[240:241] op_sel_hi:[1,0,0]
	v_cvt_pk_bf16_f32 v70, v70, v71
	v_mul_f32_e32 v76, 0x4b800000, v67
	v_cmp_gt_f32_e32 vcc, s91, v67
	v_cmp_gt_f32_e64 s[8:9], s91, v66
	s_nop 0
	v_cndmask_b32_e32 v67, v67, v76, vcc
	v_rsq_f32_e32 v67, v67
	s_nop 0
	v_mul_f32_e32 v71, 0x45800000, v67
	v_cndmask_b32_e32 v67, v67, v71, vcc
	v_cvt_pk_bf16_f32 v71, v72, v73
	v_cvt_pk_bf16_f32 v72, v74, v75
	v_cvt_pk_bf16_f32 v73, v68, v69
	s_and_b64 vcc, exec, s[6:7]
	v_mul_f32_e32 v62, v62, v67
	global_store_dwordx4 v[82:83], v[70:73], off offset:256 sc1
	s_cbranch_vccnz .LBB0_950
	v_mul_f32_e32 v68, 0x3d372713, v62
	v_mul_f32_e32 v68, v62, v68
	v_fma_f32 v68, v62, v68, v62
	v_mul_f32_e32 v68, 0xbfcc422a, v68
	v_mul_f32_e32 v68, 0x3fb8aa3b, v68
	v_exp_f32_e32 v68, v68
	s_nop 0
	v_add_f32_e32 v68, 1.0, v68
	v_rcp_f32_e32 v68, v68
	s_nop 0
	v_mul_f32_e32 v62, v62, v68

.LBB0_964:
	v_mad_i64_i32 v[68:69], s[28:29], s41, v190, 0
	v_lshl_add_u64 v[68:69], v[68:69], 1, s[14:15]
	v_cvt_pk_bf16_f32 v70, v62, v63
	v_cvt_pk_bf16_f32 v71, v64, v65
	v_cvt_pk_bf16_f32 v72, v58, v59
	v_cvt_pk_bf16_f32 v73, v60, v61
	v_lshl_add_u64 v[68:69], v[130:131], 1, v[68:69]
	global_store_dwordx4 v[68:69], v[70:73], off sc1
	s_and_saveexec_b64 s[28:29], s[26:27]
	s_cbranch_execz .LBB0_966
	v_lshl_add_u64 v[70:71], v[160:161], 0, v[188:189]
	global_store_dwordx4 v[70:71], v[62:65], off sc1
	global_store_dwordx4 v[70:71], v[58:61], off offset:16 sc1

.LBB0_982:
	v_mul_f32_e32 v52, 0x4b800000, v66
	v_cndmask_b32_e64 v52, v66, v52, s[8:9]
	v_rsq_f32_e32 v52, v52
	v_cvt_pk_bf16_f32 v54, v54, v55
	v_cvt_pk_bf16_f32 v55, v56, v57
	v_cvt_pk_bf16_f32 v56, v50, v51
	v_mul_f32_e32 v50, 0x45800000, v52
	v_cndmask_b32_e64 v52, v52, v50, s[8:9]
	v_cvt_pk_bf16_f32 v57, v58, v53
	s_and_b64 vcc, exec, s[6:7]
	v_mul_f32_e32 v46, v46, v52
	global_store_dwordx4 v[68:69], v[54:57], off offset:256 sc1
	s_cbranch_vccnz .LBB0_984
	v_mul_f32_e32 v50, 0x3d372713, v46
	v_mul_f32_e32 v50, v46, v50
	v_fma_f32 v50, v46, v50, v46
	v_mul_f32_e32 v50, 0xbfcc422a, v50
	v_mul_f32_e32 v50, 0x3fb8aa3b, v50
	v_exp_f32_e32 v50, v50
	s_nop 0
	v_add_f32_e32 v50, 1.0, v50
	v_rcp_f32_e32 v50, v50
	s_nop 0
	v_mul_f32_e32 v46, v46, v50

.LBB0_998:
	v_mad_i64_i32 v[50:51], s[8:9], s41, v186, 0
	v_lshl_add_u64 v[50:51], v[50:51], 1, s[14:15]
	v_cvt_pk_bf16_f32 v54, v46, v47
	v_cvt_pk_bf16_f32 v55, v48, v49
	v_cvt_pk_bf16_f32 v56, v42, v43
	v_cvt_pk_bf16_f32 v57, v44, v45
	v_lshl_add_u64 v[50:51], v[130:131], 1, v[50:51]
	global_store_dwordx4 v[50:51], v[54:57], off sc1
	s_and_saveexec_b64 s[8:9], s[26:27]
	s_cbranch_execz .LBB0_1000
	v_lshl_add_u64 v[54:55], v[160:161], 0, v[184:185]
	global_store_dwordx4 v[54:55], v[46:49], off sc1
	global_store_dwordx4 v[54:55], v[42:45], off offset:16 sc1

.LBB0_1016:
	s_waitcnt lgkmcnt(0)
	v_pk_add_f32 v[34:35], v[132:133], v[134:135]
	s_mov_b32 s8, 0x3a800000
	v_pk_fma_f32 v[34:35], v[34:35], s[8:9], v[240:241] op_sel_hi:[1,0,0]
	v_cvt_pk_bf16_f32 v38, v38, v39
	v_mul_f32_e32 v44, 0x4b800000, v35
	v_cmp_gt_f32_e32 vcc, s91, v35
	v_cmp_gt_f32_e64 s[8:9], s91, v34
	s_nop 0
	v_cndmask_b32_e32 v35, v35, v44, vcc
	v_rsq_f32_e32 v35, v35
	s_nop 0
	v_mul_f32_e32 v39, 0x45800000, v35
	v_cndmask_b32_e32 v35, v35, v39, vcc
	v_cvt_pk_bf16_f32 v39, v40, v41
	v_cvt_pk_bf16_f32 v40, v42, v43
	v_cvt_pk_bf16_f32 v41, v36, v37
	s_and_b64 vcc, exec, s[6:7]
	v_mul_f32_e32 v30, v30, v35
	global_store_dwordx4 v[50:51], v[38:41], off offset:256 sc1
	s_cbranch_vccnz .LBB0_1018
	v_mul_f32_e32 v36, 0x3d372713, v30
	v_mul_f32_e32 v36, v30, v36
	v_fma_f32 v36, v30, v36, v30
	v_mul_f32_e32 v36, 0xbfcc422a, v36
	v_mul_f32_e32 v36, 0x3fb8aa3b, v36
	v_exp_f32_e32 v36, v36
	s_nop 0
	v_add_f32_e32 v36, 1.0, v36
	v_rcp_f32_e32 v36, v36
	s_nop 0
	v_mul_f32_e32 v30, v30, v36

.LBB0_1032:
	v_mad_i64_i32 v[36:37], s[28:29], s41, v182, 0
	v_lshl_add_u64 v[36:37], v[36:37], 1, s[14:15]
	v_cvt_pk_bf16_f32 v38, v30, v31
	v_cvt_pk_bf16_f32 v39, v32, v33
	v_cvt_pk_bf16_f32 v40, v26, v27
	v_cvt_pk_bf16_f32 v41, v28, v29
	v_lshl_add_u64 v[36:37], v[130:131], 1, v[36:37]
	global_store_dwordx4 v[36:37], v[38:41], off sc1
	s_and_saveexec_b64 s[28:29], s[26:27]
	s_cbranch_execz .LBB0_1034
	v_lshl_add_u64 v[38:39], v[160:161], 0, v[180:181]
	global_store_dwordx4 v[38:39], v[30:33], off sc1
	global_store_dwordx4 v[38:39], v[26:29], off offset:16 sc1

.LBB0_1050:
	v_mul_f32_e32 v20, 0x4b800000, v34
	v_cndmask_b32_e64 v20, v34, v20, s[8:9]
	v_rsq_f32_e32 v20, v20
	v_cvt_pk_bf16_f32 v22, v22, v23
	v_cvt_pk_bf16_f32 v23, v24, v25
	v_cvt_pk_bf16_f32 v24, v18, v19
	v_mul_f32_e32 v18, 0x45800000, v20
	v_cndmask_b32_e64 v20, v20, v18, s[8:9]
	v_cvt_pk_bf16_f32 v25, v26, v21
	s_and_b64 vcc, exec, s[6:7]
	v_mul_f32_e32 v14, v14, v20
	global_store_dwordx4 v[36:37], v[22:25], off offset:256 sc1
	s_cbranch_vccnz .LBB0_1052
	v_mul_f32_e32 v18, 0x3d372713, v14
	v_mul_f32_e32 v18, v14, v18
	v_fma_f32 v18, v14, v18, v14
	v_mul_f32_e32 v18, 0xbfcc422a, v18
	v_mul_f32_e32 v18, 0x3fb8aa3b, v18
	v_exp_f32_e32 v18, v18
	s_nop 0
	v_add_f32_e32 v18, 1.0, v18
	v_rcp_f32_e32 v18, v18
	s_nop 0
	v_mul_f32_e32 v14, v14, v18

.LBB0_1066:
	v_mad_i64_i32 v[18:19], s[8:9], s41, v178, 0
	v_lshl_add_u64 v[18:19], v[18:19], 1, s[14:15]
	v_cvt_pk_bf16_f32 v22, v14, v15
	v_cvt_pk_bf16_f32 v23, v16, v17
	v_cvt_pk_bf16_f32 v24, v10, v11
	v_cvt_pk_bf16_f32 v25, v12, v13
	v_lshl_add_u64 v[18:19], v[130:131], 1, v[18:19]
	global_store_dwordx4 v[18:19], v[22:25], off sc1
	s_and_saveexec_b64 s[8:9], s[26:27]
	s_cbranch_execz .LBB0_1068
	v_lshl_add_u64 v[22:23], v[160:161], 0, v[176:177]
	global_store_dwordx4 v[22:23], v[14:17], off sc1
	global_store_dwordx4 v[22:23], v[10:13], off offset:16 sc1

.LBB0_1084:
	v_cvt_pk_bf16_f32 v6, v6, v7
	v_cvt_pk_bf16_f32 v7, v8, v9
	v_cvt_pk_bf16_f32 v8, v2, v3
	v_cvt_pk_bf16_f32 v9, v4, v5
	s_andn2_b64 vcc, exec, s[4:5]
	s_mov_b64 s[4:5], -1
	global_store_dwordx4 v[18:19], v[6:9], off offset:256 sc1
	s_cbranch_vccnz .LBB0_801
	s_andn2_b64 vcc, exec, s[2:3]
	s_cbranch_vccnz .LBB0_800
	s_barrier
	s_branch .LBB0_800

.LBB0_1347:
	v_lshl_add_u32 v182, s46, 8, v196
	v_lshl_or_b32 v180, s45, 8, v198
	v_readlane_b32 s6, v254, 28
	v_ashrrev_i32_e32 v181, 31, v180
	v_readlane_b32 s7, v254, 29
	v_ashrrev_i32_e32 v183, 31, v182
	v_lshlrev_b64 v[122:123], 11, v[182:183]
	v_lshl_add_u64 v[178:179], v[180:181], 1, s[6:7]
	v_or_b32_e32 v188, 16, v182
	v_lshl_add_u64 v[122:123], v[178:179], 0, v[122:123]
	v_ashrrev_i32_e32 v189, 31, v188
	global_load_dwordx4 v[200:203], v[122:123], off
	global_load_dwordx4 v[154:157], v[122:123], off offset:256
	v_lshlrev_b64 v[122:123], 11, v[188:189]
	v_or_b32_e32 v186, 32, v182
	v_lshl_add_u64 v[122:123], v[178:179], 0, v[122:123]
	v_ashrrev_i32_e32 v187, 31, v186
	global_load_dwordx4 v[150:153], v[122:123], off
	global_load_dwordx4 v[146:149], v[122:123], off offset:256
	v_lshlrev_b64 v[122:123], 11, v[186:187]
	v_or_b32_e32 v184, 48, v182
	v_lshl_add_u64 v[122:123], v[178:179], 0, v[122:123]
	v_ashrrev_i32_e32 v185, 31, v184
	global_load_dwordx4 v[142:145], v[122:123], off
	global_load_dwordx4 v[138:141], v[122:123], off offset:256
	v_lshlrev_b64 v[122:123], 11, v[184:185]
	v_lshl_add_u64 v[122:123], v[178:179], 0, v[122:123]
	global_load_dwordx4 v[134:137], v[122:123], off
	s_nop 0
	global_load_dwordx4 v[122:125], v[122:123], off offset:256
	v_lshlrev_b64 v[192:193], 10, v[182:183]
	v_lshl_add_u64 v[190:191], v[192:193], 0, v[180:181]
	s_andn2_b64 vcc, exec, s[18:19]
	v_lshl_add_u64 v[194:195], v[190:191], 2, s[2:3]
	s_waitcnt vmcnt(0)
	v_lshlrev_b32_e32 v162, 16, v200
	v_and_b32_e32 v163, 0xffff0000, v200
	v_pk_fma_f32 v[130:131], v[158:159], v[130:131], v[162:163]
	v_lshlrev_b32_e32 v162, 16, v201
	v_and_b32_e32 v163, 0xffff0000, v201
	v_pk_fma_f32 v[132:133], v[158:159], v[132:133], v[162:163]
	v_lshlrev_b32_e32 v162, 16, v202
	v_and_b32_e32 v163, 0xffff0000, v202
	v_pk_fma_f32 v[126:127], v[158:159], v[126:127], v[162:163]
	v_lshlrev_b32_e32 v162, 16, v203
	v_and_b32_e32 v163, 0xffff0000, v203
	v_pk_fma_f32 v[128:129], v[158:159], v[128:129], v[162:163]
	v_cndmask_b32_e64 v162, 0, 1, s[18:19]
	v_cmp_ne_u32_e64 s[6:7], 1, v162
	s_cbranch_vccnz .LBB0_1414
	global_store_dwordx4 v[194:195], v[130:133], off sc1
	global_store_dwordx4 v[194:195], v[126:129], off offset:16 sc1
	s_cbranch_execnz .LBB0_1350
.LBB0_1349:
	v_cvt_pk_bf16_f32 v200, v130, v131
	v_cvt_pk_bf16_f32 v201, v132, v133
	v_cvt_pk_bf16_f32 v202, v126, v127
	v_cvt_pk_bf16_f32 v203, v128, v129
	v_lshl_add_u64 v[162:163], v[192:193], 1, v[178:179]
	global_store_dwordx4 v[162:163], v[200:203], off sc1
.LBB0_1350:
	v_lshlrev_b32_e32 v162, 16, v154
	v_and_b32_e32 v163, 0xffff0000, v154
	v_lshlrev_b32_e32 v154, 16, v155
	v_and_b32_e32 v155, 0xffff0000, v155
	v_pk_fma_f32 v[120:121], v[158:159], v[120:121], v[154:155]
	v_lshlrev_b32_e32 v154, 16, v156
	v_and_b32_e32 v155, 0xffff0000, v156
	v_pk_fma_f32 v[114:115], v[158:159], v[114:115], v[154:155]
	v_lshlrev_b32_e32 v154, 16, v157
	v_and_b32_e32 v155, 0xffff0000, v157
	v_pk_fma_f32 v[118:119], v[158:159], v[118:119], v[162:163]
	s_and_b64 vcc, exec, s[6:7]
	v_pk_fma_f32 v[116:117], v[158:159], v[116:117], v[154:155]
	s_cbranch_vccnz .LBB0_1415
	global_store_dwordx4 v[194:195], v[118:121], off offset:512 sc1
	global_store_dwordx4 v[194:195], v[114:117], off offset:528 sc1
	s_cbranch_execnz .LBB0_1353
.LBB0_1352:
	v_lshlrev_b64 v[162:163], 1, v[190:191]
	v_readlane_b32 s24, v254, 28
	v_or_b32_e32 v162, 0x100, v162
	v_readlane_b32 s25, v254, 29
	v_cvt_pk_bf16_f32 v154, v118, v119
	v_cvt_pk_bf16_f32 v155, v120, v121
	v_cvt_pk_bf16_f32 v156, v114, v115
	v_cvt_pk_bf16_f32 v157, v116, v117
	v_lshl_add_u64 v[162:163], s[24:25], 0, v[162:163]
	global_store_dwordx4 v[162:163], v[154:157], off sc1
.LBB0_1353:
	v_pk_mul_f32 v[130:131], v[130:131], v[130:131]
	v_pk_mul_f32 v[132:133], v[132:133], v[132:133]
	v_add_f32_e32 v130, v130, v131
	v_add_f32_e32 v130, v132, v130
	v_pk_mul_f32 v[126:127], v[126:127], v[126:127]
	v_add_f32_e32 v130, v133, v130
	v_add_f32_e32 v126, v126, v130
	v_pk_mul_f32 v[128:129], v[128:129], v[128:129]
	v_add_f32_e32 v126, v127, v126
	v_add_f32_e32 v126, v128, v126
	v_pk_mul_f32 v[118:119], v[118:119], v[118:119]
	v_add_f32_e32 v126, v129, v126
	v_add_f32_e32 v118, v118, v126
	v_pk_mul_f32 v[120:121], v[120:121], v[120:121]
	v_add_f32_e32 v118, v119, v118
	v_add_f32_e32 v118, v120, v118
	v_pk_mul_f32 v[114:115], v[114:115], v[114:115]
	v_add_f32_e32 v118, v121, v118
	v_add_f32_e32 v114, v114, v118
	v_pk_mul_f32 v[116:117], v[116:117], v[116:117]
	v_add_f32_e32 v114, v115, v114
	v_add_f32_e32 v114, v116, v114
	v_and_b32_e32 v116, 64, v211
	v_xor_b32_e32 v115, 16, v211
	v_add_u32_e32 v116, 64, v116
	v_cmp_lt_i32_e32 vcc, v115, v116
	v_add_f32_e32 v114, v117, v114
	v_xor_b32_e32 v117, 32, v211
	v_cndmask_b32_e32 v115, v211, v115, vcc
	v_lshlrev_b32_e32 v120, 2, v115
	ds_bpermute_b32 v115, v120, v114
	v_cmp_lt_i32_e32 vcc, v117, v116
	s_lshl_b32 s24, s45, 2
	s_ashr_i32 s25, s24, 31
	v_cndmask_b32_e32 v116, v211, v117, vcc
	v_lshlrev_b32_e32 v121, 2, v116
	s_waitcnt lgkmcnt(0)
	v_add_f32_e32 v114, v114, v115
	ds_bpermute_b32 v115, v121, v114
	s_and_saveexec_b64 s[26:27], s[0:1]
	s_cbranch_execz .LBB0_1355
	v_readlane_b32 s46, v254, 30
	v_lshlrev_b64 v[116:117], 6, v[182:183]
	v_readlane_b32 s47, v254, 31
	s_lshl_b32 s92, s39, 2
	s_waitcnt lgkmcnt(0)
	v_add_f32_e32 v114, v114, v115
	v_lshl_add_u64 v[116:117], s[46:47], 0, v[116:117]
	v_lshl_add_u64 v[116:117], s[24:25], 2, v[116:117]
	v_lshl_add_u64 v[116:117], v[116:117], 0, s[92:93]
	global_store_dword v[116:117], v114, off sc1
.LBB0_1355:
	s_or_b64 exec, exec, s[26:27]
	v_lshlrev_b32_e32 v116, 16, v150
	v_and_b32_e32 v117, 0xffff0000, v150
	v_pk_fma_f32 v[110:111], v[158:159], v[110:111], v[116:117]
	v_lshlrev_b32_e32 v116, 16, v151
	v_and_b32_e32 v117, 0xffff0000, v151
	v_lshlrev_b64 v[118:119], 10, v[188:189]
	v_pk_fma_f32 v[112:113], v[158:159], v[112:113], v[116:117]
	v_lshlrev_b32_e32 v116, 16, v152
	v_and_b32_e32 v117, 0xffff0000, v152
	s_waitcnt lgkmcnt(0)
	v_lshl_add_u64 v[114:115], v[118:119], 0, v[180:181]
	v_pk_fma_f32 v[106:107], v[158:159], v[106:107], v[116:117]
	v_lshlrev_b32_e32 v116, 16, v153
	v_and_b32_e32 v117, 0xffff0000, v153
	v_pk_fma_f32 v[108:109], v[158:159], v[108:109], v[116:117]
	s_and_b64 vcc, exec, s[6:7]
	v_lshl_add_u64 v[116:117], v[114:115], 2, s[2:3]
	s_cbranch_vccnz .LBB0_1416
	global_store_dwordx4 v[116:117], v[110:113], off sc1
	global_store_dwordx4 v[116:117], v[106:109], off offset:16 sc1
	s_cbranch_execnz .LBB0_1358
.LBB0_1357:
	v_cvt_pk_bf16_f32 v126, v110, v111
	v_cvt_pk_bf16_f32 v127, v112, v113
	v_cvt_pk_bf16_f32 v128, v106, v107
	v_cvt_pk_bf16_f32 v129, v108, v109
	v_lshl_add_u64 v[118:119], v[118:119], 1, v[178:179]
	global_store_dwordx4 v[118:119], v[126:129], off sc1
.LBB0_1358:
	v_lshlrev_b32_e32 v118, 16, v146
	v_and_b32_e32 v119, 0xffff0000, v146
	v_pk_fma_f32 v[102:103], v[158:159], v[102:103], v[118:119]
	v_lshlrev_b32_e32 v118, 16, v147
	v_and_b32_e32 v119, 0xffff0000, v147
	v_pk_fma_f32 v[104:105], v[158:159], v[104:105], v[118:119]
	v_lshlrev_b32_e32 v118, 16, v148
	v_and_b32_e32 v119, 0xffff0000, v148
	v_pk_fma_f32 v[98:99], v[158:159], v[98:99], v[118:119]
	v_lshlrev_b32_e32 v118, 16, v149
	v_and_b32_e32 v119, 0xffff0000, v149
	s_and_b64 vcc, exec, s[6:7]
	v_pk_fma_f32 v[100:101], v[158:159], v[100:101], v[118:119]
	s_cbranch_vccnz .LBB0_1417
	global_store_dwordx4 v[116:117], v[102:105], off offset:512 sc1
	global_store_dwordx4 v[116:117], v[98:101], off offset:528 sc1
	s_cbranch_execnz .LBB0_1361
.LBB0_1360:
	v_lshlrev_b64 v[118:119], 1, v[114:115]
	v_readlane_b32 s26, v254, 28
	v_or_b32_e32 v118, 0x100, v118
	v_readlane_b32 s27, v254, 29
	v_cvt_pk_bf16_f32 v114, v102, v103
	v_cvt_pk_bf16_f32 v115, v104, v105
	v_cvt_pk_bf16_f32 v116, v98, v99
	v_cvt_pk_bf16_f32 v117, v100, v101
	v_lshl_add_u64 v[118:119], s[26:27], 0, v[118:119]
	global_store_dwordx4 v[118:119], v[114:117], off sc1
.LBB0_1361:
	v_pk_mul_f32 v[110:111], v[110:111], v[110:111]
	v_pk_mul_f32 v[112:113], v[112:113], v[112:113]
	v_add_f32_e32 v110, v110, v111
	v_add_f32_e32 v110, v112, v110
	v_pk_mul_f32 v[106:107], v[106:107], v[106:107]
	v_add_f32_e32 v110, v113, v110
	v_add_f32_e32 v106, v106, v110
	v_pk_mul_f32 v[108:109], v[108:109], v[108:109]
	v_add_f32_e32 v106, v107, v106
	v_add_f32_e32 v106, v108, v106
	v_pk_mul_f32 v[102:103], v[102:103], v[102:103]
	v_add_f32_e32 v106, v109, v106
	v_add_f32_e32 v102, v102, v106
	v_pk_mul_f32 v[104:105], v[104:105], v[104:105]
	v_add_f32_e32 v102, v103, v102
	v_add_f32_e32 v102, v104, v102
	v_pk_mul_f32 v[98:99], v[98:99], v[98:99]
	v_add_f32_e32 v102, v105, v102
	v_add_f32_e32 v98, v98, v102
	v_pk_mul_f32 v[100:101], v[100:101], v[100:101]
	v_add_f32_e32 v98, v99, v98
	v_add_f32_e32 v98, v100, v98
	v_add_f32_e32 v98, v101, v98
	ds_bpermute_b32 v99, v120, v98
	s_waitcnt lgkmcnt(0)
	v_add_f32_e32 v98, v98, v99
	ds_bpermute_b32 v99, v121, v98
	s_and_saveexec_b64 s[26:27], s[0:1]
	s_cbranch_execz .LBB0_1363
	v_readlane_b32 s46, v254, 30
	v_lshlrev_b64 v[100:101], 6, v[188:189]
	v_readlane_b32 s47, v254, 31
	s_lshl_b32 s92, s39, 2
	s_waitcnt lgkmcnt(0)
	v_add_f32_e32 v98, v98, v99
	v_lshl_add_u64 v[100:101], s[46:47], 0, v[100:101]
	v_lshl_add_u64 v[100:101], s[24:25], 2, v[100:101]
	v_lshl_add_u64 v[100:101], v[100:101], 0, s[92:93]
	global_store_dword v[100:101], v98, off sc1
.LBB0_1363:
	s_or_b64 exec, exec, s[26:27]
	v_lshlrev_b32_e32 v100, 16, v142
	v_and_b32_e32 v101, 0xffff0000, v142
	v_pk_fma_f32 v[94:95], v[158:159], v[94:95], v[100:101]
	v_lshlrev_b32_e32 v100, 16, v143
	v_and_b32_e32 v101, 0xffff0000, v143
	v_lshlrev_b64 v[102:103], 10, v[186:187]
	v_pk_fma_f32 v[96:97], v[158:159], v[96:97], v[100:101]
	v_lshlrev_b32_e32 v100, 16, v144
	v_and_b32_e32 v101, 0xffff0000, v144
	s_waitcnt lgkmcnt(0)
	v_lshl_add_u64 v[98:99], v[102:103], 0, v[180:181]
	v_pk_fma_f32 v[90:91], v[158:159], v[90:91], v[100:101]
	v_lshlrev_b32_e32 v100, 16, v145
	v_and_b32_e32 v101, 0xffff0000, v145
	v_pk_fma_f32 v[92:93], v[158:159], v[92:93], v[100:101]
	s_and_b64 vcc, exec, s[6:7]
	v_lshl_add_u64 v[100:101], v[98:99], 2, s[2:3]
	s_cbranch_vccnz .LBB0_1418
	global_store_dwordx4 v[100:101], v[94:97], off sc1
	global_store_dwordx4 v[100:101], v[90:93], off offset:16 sc1
	s_cbranch_execnz .LBB0_1366
.LBB0_1365:
	v_cvt_pk_bf16_f32 v104, v94, v95
	v_cvt_pk_bf16_f32 v105, v96, v97
	v_cvt_pk_bf16_f32 v106, v90, v91
	v_cvt_pk_bf16_f32 v107, v92, v93
	v_lshl_add_u64 v[102:103], v[102:103], 1, v[178:179]
	global_store_dwordx4 v[102:103], v[104:107], off sc1
.LBB0_1366:
	v_lshlrev_b32_e32 v102, 16, v138
	v_and_b32_e32 v103, 0xffff0000, v138
	v_pk_fma_f32 v[86:87], v[158:159], v[86:87], v[102:103]
	v_lshlrev_b32_e32 v102, 16, v139
	v_and_b32_e32 v103, 0xffff0000, v139
	v_pk_fma_f32 v[88:89], v[158:159], v[88:89], v[102:103]
	v_lshlrev_b32_e32 v102, 16, v140
	v_and_b32_e32 v103, 0xffff0000, v140
	v_pk_fma_f32 v[82:83], v[158:159], v[82:83], v[102:103]
	v_lshlrev_b32_e32 v102, 16, v141
	v_and_b32_e32 v103, 0xffff0000, v141
	s_and_b64 vcc, exec, s[6:7]
	v_pk_fma_f32 v[84:85], v[158:159], v[84:85], v[102:103]
	s_cbranch_vccnz .LBB0_1419
	global_store_dwordx4 v[100:101], v[86:89], off offset:512 sc1
	global_store_dwordx4 v[100:101], v[82:85], off offset:528 sc1
	s_cbranch_execnz .LBB0_1369
.LBB0_1368:
	v_lshlrev_b64 v[102:103], 1, v[98:99]
	v_readlane_b32 s26, v254, 28
	v_or_b32_e32 v102, 0x100, v102
	v_readlane_b32 s27, v254, 29
	v_cvt_pk_bf16_f32 v98, v86, v87
	v_cvt_pk_bf16_f32 v99, v88, v89
	v_cvt_pk_bf16_f32 v100, v82, v83
	v_cvt_pk_bf16_f32 v101, v84, v85
	v_lshl_add_u64 v[102:103], s[26:27], 0, v[102:103]
	global_store_dwordx4 v[102:103], v[98:101], off sc1
.LBB0_1369:
	v_pk_mul_f32 v[94:95], v[94:95], v[94:95]
	v_pk_mul_f32 v[96:97], v[96:97], v[96:97]
	v_add_f32_e32 v94, v94, v95
	v_add_f32_e32 v94, v96, v94
	v_pk_mul_f32 v[90:91], v[90:91], v[90:91]
	v_add_f32_e32 v94, v97, v94
	v_add_f32_e32 v90, v90, v94
	v_pk_mul_f32 v[92:93], v[92:93], v[92:93]
	v_add_f32_e32 v90, v91, v90
	v_add_f32_e32 v90, v92, v90
	v_pk_mul_f32 v[86:87], v[86:87], v[86:87]
	v_add_f32_e32 v90, v93, v90
	v_add_f32_e32 v86, v86, v90
	v_pk_mul_f32 v[88:89], v[88:89], v[88:89]
	v_add_f32_e32 v86, v87, v86
	v_add_f32_e32 v86, v88, v86
	v_pk_mul_f32 v[82:83], v[82:83], v[82:83]
	v_add_f32_e32 v86, v89, v86
	v_add_f32_e32 v82, v82, v86
	v_pk_mul_f32 v[84:85], v[84:85], v[84:85]
	v_add_f32_e32 v82, v83, v82
	v_add_f32_e32 v82, v84, v82
	v_add_f32_e32 v82, v85, v82
	ds_bpermute_b32 v83, v120, v82
	s_waitcnt lgkmcnt(0)
	v_add_f32_e32 v82, v82, v83
	ds_bpermute_b32 v83, v121, v82
	s_and_saveexec_b64 s[26:27], s[0:1]
	s_cbranch_execz .LBB0_1371
	v_readlane_b32 s46, v254, 30
	v_lshlrev_b64 v[84:85], 6, v[186:187]
	v_readlane_b32 s47, v254, 31
	s_lshl_b32 s92, s39, 2
	s_waitcnt lgkmcnt(0)
	v_add_f32_e32 v82, v82, v83
	v_lshl_add_u64 v[84:85], s[46:47], 0, v[84:85]
	v_lshl_add_u64 v[84:85], s[24:25], 2, v[84:85]
	v_lshl_add_u64 v[84:85], v[84:85], 0, s[92:93]
	global_store_dword v[84:85], v82, off sc1
.LBB0_1371:
	s_or_b64 exec, exec, s[26:27]
	v_lshlrev_b32_e32 v84, 16, v134
	v_and_b32_e32 v85, 0xffff0000, v134
	v_pk_fma_f32 v[78:79], v[158:159], v[78:79], v[84:85]
	v_lshlrev_b32_e32 v84, 16, v135
	v_and_b32_e32 v85, 0xffff0000, v135
	v_lshlrev_b64 v[86:87], 10, v[184:185]
	v_pk_fma_f32 v[80:81], v[158:159], v[80:81], v[84:85]
	v_lshlrev_b32_e32 v84, 16, v136
	v_and_b32_e32 v85, 0xffff0000, v136
	s_waitcnt lgkmcnt(0)
	v_lshl_add_u64 v[82:83], v[86:87], 0, v[180:181]
	v_pk_fma_f32 v[74:75], v[158:159], v[74:75], v[84:85]
	v_lshlrev_b32_e32 v84, 16, v137
	v_and_b32_e32 v85, 0xffff0000, v137
	v_pk_fma_f32 v[76:77], v[158:159], v[76:77], v[84:85]
	s_and_b64 vcc, exec, s[6:7]
	v_lshl_add_u64 v[84:85], v[82:83], 2, s[2:3]
	s_cbranch_vccnz .LBB0_1420
	global_store_dwordx4 v[84:85], v[78:81], off sc1
	global_store_dwordx4 v[84:85], v[74:77], off offset:16 sc1
	s_cbranch_execnz .LBB0_1374
.LBB0_1373:
	v_cvt_pk_bf16_f32 v88, v78, v79
	v_cvt_pk_bf16_f32 v89, v80, v81
	v_cvt_pk_bf16_f32 v90, v74, v75
	v_cvt_pk_bf16_f32 v91, v76, v77
	v_lshl_add_u64 v[86:87], v[86:87], 1, v[178:179]
	global_store_dwordx4 v[86:87], v[88:91], off sc1
.LBB0_1374:
	v_lshlrev_b32_e32 v86, 16, v122
	v_and_b32_e32 v87, 0xffff0000, v122
	v_pk_fma_f32 v[70:71], v[158:159], v[70:71], v[86:87]
	v_lshlrev_b32_e32 v86, 16, v123
	v_and_b32_e32 v87, 0xffff0000, v123
	v_pk_fma_f32 v[72:73], v[158:159], v[72:73], v[86:87]
	v_lshlrev_b32_e32 v86, 16, v124
	v_and_b32_e32 v87, 0xffff0000, v124
	v_pk_fma_f32 v[66:67], v[158:159], v[66:67], v[86:87]
	v_lshlrev_b32_e32 v86, 16, v125
	v_and_b32_e32 v87, 0xffff0000, v125
	s_and_b64 vcc, exec, s[6:7]
	v_pk_fma_f32 v[68:69], v[158:159], v[68:69], v[86:87]
	s_cbranch_vccnz .LBB0_1421
	global_store_dwordx4 v[84:85], v[70:73], off offset:512 sc1
	global_store_dwordx4 v[84:85], v[66:69], off offset:528 sc1
	s_cbranch_execnz .LBB0_1377
.LBB0_1376:
	v_lshlrev_b64 v[86:87], 1, v[82:83]
	v_readlane_b32 s26, v254, 28
	v_or_b32_e32 v86, 0x100, v86
	v_readlane_b32 s27, v254, 29
	v_cvt_pk_bf16_f32 v82, v70, v71
	v_cvt_pk_bf16_f32 v83, v72, v73
	v_cvt_pk_bf16_f32 v84, v66, v67
	v_cvt_pk_bf16_f32 v85, v68, v69
	v_lshl_add_u64 v[86:87], s[26:27], 0, v[86:87]
	global_store_dwordx4 v[86:87], v[82:85], off sc1
.LBB0_1377:
	v_pk_mul_f32 v[78:79], v[78:79], v[78:79]
	v_pk_mul_f32 v[80:81], v[80:81], v[80:81]
	v_add_f32_e32 v78, v78, v79
	v_add_f32_e32 v78, v80, v78
	v_pk_mul_f32 v[74:75], v[74:75], v[74:75]
	v_add_f32_e32 v78, v81, v78
	v_add_f32_e32 v74, v74, v78
	v_pk_mul_f32 v[76:77], v[76:77], v[76:77]
	v_add_f32_e32 v74, v75, v74
	v_add_f32_e32 v74, v76, v74
	v_pk_mul_f32 v[70:71], v[70:71], v[70:71]
	v_add_f32_e32 v74, v77, v74
	v_add_f32_e32 v70, v70, v74
	v_pk_mul_f32 v[72:73], v[72:73], v[72:73]
	v_add_f32_e32 v70, v71, v70
	v_add_f32_e32 v70, v72, v70
	v_pk_mul_f32 v[66:67], v[66:67], v[66:67]
	v_add_f32_e32 v70, v73, v70
	v_add_f32_e32 v66, v66, v70
	v_pk_mul_f32 v[68:69], v[68:69], v[68:69]
	v_add_f32_e32 v66, v67, v66
	v_add_f32_e32 v66, v68, v66
	v_add_f32_e32 v66, v69, v66
	ds_bpermute_b32 v67, v120, v66
	s_waitcnt lgkmcnt(0)
	v_add_f32_e32 v66, v66, v67
	ds_bpermute_b32 v67, v121, v66
	s_and_saveexec_b64 s[26:27], s[0:1]
	s_cbranch_execz .LBB0_1379
	v_readlane_b32 s46, v254, 30
	v_lshlrev_b64 v[68:69], 6, v[184:185]
	v_readlane_b32 s47, v254, 31
	s_lshl_b32 s92, s39, 2
	s_waitcnt lgkmcnt(0)
	v_add_f32_e32 v66, v66, v67
	v_lshl_add_u64 v[68:69], s[46:47], 0, v[68:69]
	v_lshl_add_u64 v[68:69], s[24:25], 2, v[68:69]
	v_lshl_add_u64 v[68:69], v[68:69], 0, s[92:93]
	global_store_dword v[68:69], v66, off sc1
.LBB0_1379:
	s_or_b64 exec, exec, s[26:27]
	v_add_u32_e32 v100, 0x80, v182
	v_ashrrev_i32_e32 v101, 31, v100
	s_waitcnt lgkmcnt(0)
	v_lshlrev_b64 v[66:67], 11, v[100:101]
	v_add_u32_e32 v98, 0x90, v182
	v_lshl_add_u64 v[66:67], v[178:179], 0, v[66:67]
	v_ashrrev_i32_e32 v99, 31, v98
	global_load_dwordx4 v[106:109], v[66:67], off
	global_load_dwordx4 v[90:93], v[66:67], off offset:256
	v_lshlrev_b64 v[66:67], 11, v[98:99]
	v_add_u32_e32 v96, 0xa0, v182
	v_lshl_add_u64 v[66:67], v[178:179], 0, v[66:67]
	v_ashrrev_i32_e32 v97, 31, v96
	global_load_dwordx4 v[86:89], v[66:67], off
	global_load_dwordx4 v[82:85], v[66:67], off offset:256
	v_lshlrev_b64 v[66:67], 11, v[96:97]
	v_add_u32_e32 v94, 0xb0, v182
	v_lshl_add_u64 v[66:67], v[178:179], 0, v[66:67]
	v_ashrrev_i32_e32 v95, 31, v94
	global_load_dwordx4 v[78:81], v[66:67], off
	global_load_dwordx4 v[74:77], v[66:67], off offset:256
	v_lshlrev_b64 v[66:67], 11, v[94:95]
	v_lshl_add_u64 v[66:67], v[178:179], 0, v[66:67]
	global_load_dwordx4 v[70:73], v[66:67], off
	s_nop 0
	global_load_dwordx4 v[66:69], v[66:67], off offset:256
	v_lshlrev_b64 v[104:105], 10, v[100:101]
	v_lshl_add_u64 v[102:103], v[104:105], 0, v[180:181]
	s_and_b64 vcc, exec, s[6:7]
	s_waitcnt vmcnt(7)
	v_lshlrev_b32_e32 v110, 16, v106
	v_and_b32_e32 v111, 0xffff0000, v106
	v_lshlrev_b32_e32 v106, 16, v107
	v_and_b32_e32 v107, 0xffff0000, v107
	v_pk_fma_f32 v[64:65], v[158:159], v[64:65], v[106:107]
	v_lshlrev_b32_e32 v106, 16, v108
	v_and_b32_e32 v107, 0xffff0000, v108
	v_pk_fma_f32 v[58:59], v[158:159], v[58:59], v[106:107]
	v_lshlrev_b32_e32 v106, 16, v109
	v_and_b32_e32 v107, 0xffff0000, v109
	v_pk_fma_f32 v[62:63], v[158:159], v[62:63], v[110:111]
	v_pk_fma_f32 v[60:61], v[158:159], v[60:61], v[106:107]
	v_lshl_add_u64 v[106:107], v[102:103], 2, s[2:3]
	s_cbranch_vccnz .LBB0_1422
	global_store_dwordx4 v[106:107], v[62:65], off sc1
	global_store_dwordx4 v[106:107], v[58:61], off offset:16 sc1
	s_cbranch_execnz .LBB0_1382
.LBB0_1381:
	v_cvt_pk_bf16_f32 v108, v62, v63
	v_cvt_pk_bf16_f32 v109, v64, v65
	v_cvt_pk_bf16_f32 v110, v58, v59
	v_cvt_pk_bf16_f32 v111, v60, v61
	v_lshl_add_u64 v[104:105], v[104:105], 1, v[178:179]
	global_store_dwordx4 v[104:105], v[108:111], off sc1
.LBB0_1382:
	s_waitcnt vmcnt(6)
	v_lshlrev_b32_e32 v104, 16, v90
	v_and_b32_e32 v105, 0xffff0000, v90
	v_lshlrev_b32_e32 v90, 16, v91
	v_and_b32_e32 v91, 0xffff0000, v91
	v_pk_fma_f32 v[56:57], v[158:159], v[56:57], v[90:91]
	v_lshlrev_b32_e32 v90, 16, v92
	v_and_b32_e32 v91, 0xffff0000, v92
	v_pk_fma_f32 v[50:51], v[158:159], v[50:51], v[90:91]
	v_lshlrev_b32_e32 v90, 16, v93
	v_and_b32_e32 v91, 0xffff0000, v93
	v_pk_fma_f32 v[54:55], v[158:159], v[54:55], v[104:105]
	s_and_b64 vcc, exec, s[6:7]
	v_pk_fma_f32 v[52:53], v[158:159], v[52:53], v[90:91]
	s_cbranch_vccnz .LBB0_1423
	global_store_dwordx4 v[106:107], v[54:57], off offset:512 sc1
	global_store_dwordx4 v[106:107], v[50:53], off offset:528 sc1
	s_cbranch_execnz .LBB0_1385
.LBB0_1384:
	v_lshlrev_b64 v[102:103], 1, v[102:103]
	v_readlane_b32 s26, v254, 28
	v_or_b32_e32 v102, 0x100, v102
	v_readlane_b32 s27, v254, 29
	v_cvt_pk_bf16_f32 v90, v54, v55
	v_cvt_pk_bf16_f32 v91, v56, v57
	v_cvt_pk_bf16_f32 v92, v50, v51
	v_cvt_pk_bf16_f32 v93, v52, v53
	v_lshl_add_u64 v[102:103], s[26:27], 0, v[102:103]
	global_store_dwordx4 v[102:103], v[90:93], off sc1
.LBB0_1385:
	v_pk_mul_f32 v[62:63], v[62:63], v[62:63]
	v_pk_mul_f32 v[64:65], v[64:65], v[64:65]
	v_add_f32_e32 v62, v62, v63
	v_add_f32_e32 v62, v64, v62
	v_pk_mul_f32 v[58:59], v[58:59], v[58:59]
	v_add_f32_e32 v62, v65, v62
	v_add_f32_e32 v58, v58, v62
	v_pk_mul_f32 v[60:61], v[60:61], v[60:61]
	v_add_f32_e32 v58, v59, v58
	v_add_f32_e32 v58, v60, v58
	v_pk_mul_f32 v[54:55], v[54:55], v[54:55]
	v_add_f32_e32 v58, v61, v58
	v_add_f32_e32 v54, v54, v58
	v_pk_mul_f32 v[56:57], v[56:57], v[56:57]
	v_add_f32_e32 v54, v55, v54
	v_add_f32_e32 v54, v56, v54
	v_pk_mul_f32 v[50:51], v[50:51], v[50:51]
	v_add_f32_e32 v54, v57, v54
	v_add_f32_e32 v50, v50, v54
	v_pk_mul_f32 v[52:53], v[52:53], v[52:53]
	v_add_f32_e32 v50, v51, v50
	v_add_f32_e32 v50, v52, v50
	v_add_f32_e32 v50, v53, v50
	ds_bpermute_b32 v51, v120, v50
	s_waitcnt lgkmcnt(0)
	v_add_f32_e32 v50, v50, v51
	ds_bpermute_b32 v51, v121, v50
	s_and_saveexec_b64 s[26:27], s[0:1]
	s_cbranch_execz .LBB0_1387
	v_readlane_b32 s46, v254, 30
	v_lshlrev_b64 v[52:53], 6, v[100:101]
	v_readlane_b32 s47, v254, 31
	s_lshl_b32 s92, s39, 2
	s_waitcnt lgkmcnt(0)
	v_add_f32_e32 v50, v50, v51
	v_lshl_add_u64 v[52:53], s[46:47], 0, v[52:53]
	v_lshl_add_u64 v[52:53], s[24:25], 2, v[52:53]
	v_lshl_add_u64 v[52:53], v[52:53], 0, s[92:93]
	global_store_dword v[52:53], v50, off sc1
.LBB0_1387:
	s_or_b64 exec, exec, s[26:27]
	s_waitcnt vmcnt(5)
	v_lshlrev_b32_e32 v52, 16, v86
	v_and_b32_e32 v53, 0xffff0000, v86
	v_pk_fma_f32 v[46:47], v[158:159], v[46:47], v[52:53]
	v_lshlrev_b32_e32 v52, 16, v87
	v_and_b32_e32 v53, 0xffff0000, v87
	v_lshlrev_b64 v[54:55], 10, v[98:99]
	v_pk_fma_f32 v[48:49], v[158:159], v[48:49], v[52:53]
	v_lshlrev_b32_e32 v52, 16, v88
	v_and_b32_e32 v53, 0xffff0000, v88
	s_waitcnt lgkmcnt(0)
	v_lshl_add_u64 v[50:51], v[54:55], 0, v[180:181]
	v_pk_fma_f32 v[42:43], v[158:159], v[42:43], v[52:53]
	v_lshlrev_b32_e32 v52, 16, v89
	v_and_b32_e32 v53, 0xffff0000, v89
	v_pk_fma_f32 v[44:45], v[158:159], v[44:45], v[52:53]
	s_and_b64 vcc, exec, s[6:7]
	v_lshl_add_u64 v[52:53], v[50:51], 2, s[2:3]
	s_cbranch_vccnz .LBB0_1424
	global_store_dwordx4 v[52:53], v[46:49], off sc1
	global_store_dwordx4 v[52:53], v[42:45], off offset:16 sc1
	s_cbranch_execnz .LBB0_1390
.LBB0_1389:
	v_cvt_pk_bf16_f32 v56, v46, v47
	v_cvt_pk_bf16_f32 v57, v48, v49
	v_cvt_pk_bf16_f32 v58, v42, v43
	v_cvt_pk_bf16_f32 v59, v44, v45
	v_lshl_add_u64 v[54:55], v[54:55], 1, v[178:179]
	global_store_dwordx4 v[54:55], v[56:59], off sc1
.LBB0_1390:
	s_waitcnt vmcnt(4)
	v_lshlrev_b32_e32 v54, 16, v82
	v_and_b32_e32 v55, 0xffff0000, v82
	v_pk_fma_f32 v[38:39], v[158:159], v[38:39], v[54:55]
	v_lshlrev_b32_e32 v54, 16, v83
	v_and_b32_e32 v55, 0xffff0000, v83
	v_pk_fma_f32 v[40:41], v[158:159], v[40:41], v[54:55]
	v_lshlrev_b32_e32 v54, 16, v84
	v_and_b32_e32 v55, 0xffff0000, v84
	v_pk_fma_f32 v[34:35], v[158:159], v[34:35], v[54:55]
	v_lshlrev_b32_e32 v54, 16, v85
	v_and_b32_e32 v55, 0xffff0000, v85
	s_and_b64 vcc, exec, s[6:7]
	v_pk_fma_f32 v[36:37], v[158:159], v[36:37], v[54:55]
	s_cbranch_vccnz .LBB0_1425
	global_store_dwordx4 v[52:53], v[38:41], off offset:512 sc1
	global_store_dwordx4 v[52:53], v[34:37], off offset:528 sc1
	s_cbranch_execnz .LBB0_1393
.LBB0_1392:
	v_lshlrev_b64 v[54:55], 1, v[50:51]
	v_readlane_b32 s26, v254, 28
	v_or_b32_e32 v54, 0x100, v54
	v_readlane_b32 s27, v254, 29
	v_cvt_pk_bf16_f32 v50, v38, v39
	v_cvt_pk_bf16_f32 v51, v40, v41
	v_cvt_pk_bf16_f32 v52, v34, v35
	v_cvt_pk_bf16_f32 v53, v36, v37
	v_lshl_add_u64 v[54:55], s[26:27], 0, v[54:55]
	global_store_dwordx4 v[54:55], v[50:53], off sc1
.LBB0_1393:
	v_pk_mul_f32 v[46:47], v[46:47], v[46:47]
	v_pk_mul_f32 v[48:49], v[48:49], v[48:49]
	v_add_f32_e32 v46, v46, v47
	v_add_f32_e32 v46, v48, v46
	v_pk_mul_f32 v[42:43], v[42:43], v[42:43]
	v_add_f32_e32 v46, v49, v46
	v_add_f32_e32 v42, v42, v46
	v_pk_mul_f32 v[44:45], v[44:45], v[44:45]
	v_add_f32_e32 v42, v43, v42
	v_add_f32_e32 v42, v44, v42
	v_pk_mul_f32 v[38:39], v[38:39], v[38:39]
	v_add_f32_e32 v42, v45, v42
	v_add_f32_e32 v38, v38, v42
	v_pk_mul_f32 v[40:41], v[40:41], v[40:41]
	v_add_f32_e32 v38, v39, v38
	v_add_f32_e32 v38, v40, v38
	v_pk_mul_f32 v[34:35], v[34:35], v[34:35]
	v_add_f32_e32 v38, v41, v38
	v_add_f32_e32 v34, v34, v38
	v_pk_mul_f32 v[36:37], v[36:37], v[36:37]
	v_add_f32_e32 v34, v35, v34
	v_add_f32_e32 v34, v36, v34
	v_add_f32_e32 v34, v37, v34
	ds_bpermute_b32 v35, v120, v34
	s_waitcnt lgkmcnt(0)
	v_add_f32_e32 v34, v34, v35
	ds_bpermute_b32 v35, v121, v34
	s_and_saveexec_b64 s[26:27], s[0:1]
	s_cbranch_execz .LBB0_1395
	v_readlane_b32 s46, v254, 30
	v_lshlrev_b64 v[36:37], 6, v[98:99]
	v_readlane_b32 s47, v254, 31
	s_lshl_b32 s92, s39, 2
	s_waitcnt lgkmcnt(0)
	v_add_f32_e32 v34, v34, v35
	v_lshl_add_u64 v[36:37], s[46:47], 0, v[36:37]
	v_lshl_add_u64 v[36:37], s[24:25], 2, v[36:37]
	v_lshl_add_u64 v[36:37], v[36:37], 0, s[92:93]
	global_store_dword v[36:37], v34, off sc1
.LBB0_1395:
	s_or_b64 exec, exec, s[26:27]
	s_waitcnt vmcnt(3)
	v_lshlrev_b32_e32 v36, 16, v78
	v_and_b32_e32 v37, 0xffff0000, v78
	v_pk_fma_f32 v[30:31], v[158:159], v[30:31], v[36:37]
	v_lshlrev_b32_e32 v36, 16, v79
	v_and_b32_e32 v37, 0xffff0000, v79
	v_lshlrev_b64 v[38:39], 10, v[96:97]
	v_pk_fma_f32 v[32:33], v[158:159], v[32:33], v[36:37]
	v_lshlrev_b32_e32 v36, 16, v80
	v_and_b32_e32 v37, 0xffff0000, v80
	s_waitcnt lgkmcnt(0)
	v_lshl_add_u64 v[34:35], v[38:39], 0, v[180:181]
	v_pk_fma_f32 v[26:27], v[158:159], v[26:27], v[36:37]
	v_lshlrev_b32_e32 v36, 16, v81
	v_and_b32_e32 v37, 0xffff0000, v81
	v_pk_fma_f32 v[28:29], v[158:159], v[28:29], v[36:37]
	s_and_b64 vcc, exec, s[6:7]
	v_lshl_add_u64 v[36:37], v[34:35], 2, s[2:3]
	s_cbranch_vccnz .LBB0_1426
	global_store_dwordx4 v[36:37], v[30:33], off sc1
	global_store_dwordx4 v[36:37], v[26:29], off offset:16 sc1
	s_cbranch_execnz .LBB0_1398
.LBB0_1397:
	v_cvt_pk_bf16_f32 v40, v30, v31
	v_cvt_pk_bf16_f32 v41, v32, v33
	v_cvt_pk_bf16_f32 v42, v26, v27
	v_cvt_pk_bf16_f32 v43, v28, v29
	v_lshl_add_u64 v[38:39], v[38:39], 1, v[178:179]
	global_store_dwordx4 v[38:39], v[40:43], off sc1
.LBB0_1398:
	s_waitcnt vmcnt(2)
	v_lshlrev_b32_e32 v38, 16, v74
	v_and_b32_e32 v39, 0xffff0000, v74
	v_pk_fma_f32 v[22:23], v[158:159], v[22:23], v[38:39]
	v_lshlrev_b32_e32 v38, 16, v75
	v_and_b32_e32 v39, 0xffff0000, v75
	v_pk_fma_f32 v[24:25], v[158:159], v[24:25], v[38:39]
	v_lshlrev_b32_e32 v38, 16, v76
	v_and_b32_e32 v39, 0xffff0000, v76
	v_pk_fma_f32 v[18:19], v[158:159], v[18:19], v[38:39]
	v_lshlrev_b32_e32 v38, 16, v77
	v_and_b32_e32 v39, 0xffff0000, v77
	s_and_b64 vcc, exec, s[6:7]
	v_pk_fma_f32 v[20:21], v[158:159], v[20:21], v[38:39]
	s_cbranch_vccnz .LBB0_1427
	global_store_dwordx4 v[36:37], v[22:25], off offset:512 sc1
	global_store_dwordx4 v[36:37], v[18:21], off offset:528 sc1
	s_cbranch_execnz .LBB0_1401
.LBB0_1400:
	v_lshlrev_b64 v[38:39], 1, v[34:35]
	v_readlane_b32 s26, v254, 28
	v_or_b32_e32 v38, 0x100, v38
	v_readlane_b32 s27, v254, 29
	v_cvt_pk_bf16_f32 v34, v22, v23
	v_cvt_pk_bf16_f32 v35, v24, v25
	v_cvt_pk_bf16_f32 v36, v18, v19
	v_cvt_pk_bf16_f32 v37, v20, v21
	v_lshl_add_u64 v[38:39], s[26:27], 0, v[38:39]
	global_store_dwordx4 v[38:39], v[34:37], off sc1
.LBB0_1401:
	v_pk_mul_f32 v[30:31], v[30:31], v[30:31]
	v_pk_mul_f32 v[32:33], v[32:33], v[32:33]
	v_add_f32_e32 v30, v30, v31
	v_add_f32_e32 v30, v32, v30
	v_pk_mul_f32 v[26:27], v[26:27], v[26:27]
	v_add_f32_e32 v30, v33, v30
	v_add_f32_e32 v26, v26, v30
	v_pk_mul_f32 v[28:29], v[28:29], v[28:29]
	v_add_f32_e32 v26, v27, v26
	v_add_f32_e32 v26, v28, v26
	v_pk_mul_f32 v[22:23], v[22:23], v[22:23]
	v_add_f32_e32 v26, v29, v26
	v_add_f32_e32 v22, v22, v26
	v_pk_mul_f32 v[24:25], v[24:25], v[24:25]
	v_add_f32_e32 v22, v23, v22
	v_add_f32_e32 v22, v24, v22
	v_pk_mul_f32 v[18:19], v[18:19], v[18:19]
	v_add_f32_e32 v22, v25, v22
	v_add_f32_e32 v18, v18, v22
	v_pk_mul_f32 v[20:21], v[20:21], v[20:21]
	v_add_f32_e32 v18, v19, v18
	v_add_f32_e32 v18, v20, v18
	v_add_f32_e32 v18, v21, v18
	ds_bpermute_b32 v19, v120, v18
	s_waitcnt lgkmcnt(0)
	v_add_f32_e32 v18, v18, v19
	ds_bpermute_b32 v19, v121, v18
	s_and_saveexec_b64 s[26:27], s[0:1]
	s_cbranch_execz .LBB0_1403
	v_readlane_b32 s46, v254, 30
	v_lshlrev_b64 v[20:21], 6, v[96:97]
	v_readlane_b32 s47, v254, 31
	s_lshl_b32 s92, s39, 2
	s_waitcnt lgkmcnt(0)
	v_add_f32_e32 v18, v18, v19
	v_lshl_add_u64 v[20:21], s[46:47], 0, v[20:21]
	v_lshl_add_u64 v[20:21], s[24:25], 2, v[20:21]
	v_lshl_add_u64 v[20:21], v[20:21], 0, s[92:93]
	global_store_dword v[20:21], v18, off sc1
.LBB0_1403:
	s_or_b64 exec, exec, s[26:27]
	s_waitcnt vmcnt(1)
	v_lshlrev_b32_e32 v20, 16, v70
	v_and_b32_e32 v21, 0xffff0000, v70
	v_pk_fma_f32 v[14:15], v[158:159], v[14:15], v[20:21]
	v_lshlrev_b32_e32 v20, 16, v71
	v_and_b32_e32 v21, 0xffff0000, v71
	v_lshlrev_b64 v[22:23], 10, v[94:95]
	v_pk_fma_f32 v[16:17], v[158:159], v[16:17], v[20:21]
	v_lshlrev_b32_e32 v20, 16, v72
	v_and_b32_e32 v21, 0xffff0000, v72
	s_waitcnt lgkmcnt(0)
	v_lshl_add_u64 v[18:19], v[22:23], 0, v[180:181]
	v_pk_fma_f32 v[10:11], v[158:159], v[10:11], v[20:21]
	v_lshlrev_b32_e32 v20, 16, v73
	v_and_b32_e32 v21, 0xffff0000, v73
	v_pk_fma_f32 v[12:13], v[158:159], v[12:13], v[20:21]
	s_and_b64 vcc, exec, s[6:7]
	v_lshl_add_u64 v[20:21], v[18:19], 2, s[2:3]
	s_cbranch_vccnz .LBB0_1428
	global_store_dwordx4 v[20:21], v[14:17], off sc1
	global_store_dwordx4 v[20:21], v[10:13], off offset:16 sc1
	s_cbranch_execnz .LBB0_1406
.LBB0_1405:
	v_cvt_pk_bf16_f32 v24, v14, v15
	v_cvt_pk_bf16_f32 v25, v16, v17
	v_cvt_pk_bf16_f32 v26, v10, v11
	v_cvt_pk_bf16_f32 v27, v12, v13
	v_lshl_add_u64 v[22:23], v[22:23], 1, v[178:179]
	global_store_dwordx4 v[22:23], v[24:27], off sc1
.LBB0_1406:
	s_waitcnt vmcnt(0)
	v_lshlrev_b32_e32 v22, 16, v66
	v_and_b32_e32 v23, 0xffff0000, v66
	v_pk_fma_f32 v[6:7], v[158:159], v[6:7], v[22:23]
	v_lshlrev_b32_e32 v22, 16, v67
	v_and_b32_e32 v23, 0xffff0000, v67
	v_pk_fma_f32 v[8:9], v[158:159], v[8:9], v[22:23]
	v_lshlrev_b32_e32 v22, 16, v68
	v_and_b32_e32 v23, 0xffff0000, v68
	v_pk_fma_f32 v[2:3], v[158:159], v[2:3], v[22:23]
	v_lshlrev_b32_e32 v22, 16, v69
	v_and_b32_e32 v23, 0xffff0000, v69
	s_and_b64 vcc, exec, s[6:7]
	v_pk_fma_f32 v[4:5], v[158:159], v[4:5], v[22:23]
	s_cbranch_vccnz .LBB0_1429
	global_store_dwordx4 v[20:21], v[6:9], off offset:512 sc1
	global_store_dwordx4 v[20:21], v[2:5], off offset:528 sc1
	s_cbranch_execnz .LBB0_1409
.LBB0_1408:
	v_lshlrev_b64 v[22:23], 1, v[18:19]
	v_readlane_b32 s6, v254, 28
	v_or_b32_e32 v22, 0x100, v22
	v_readlane_b32 s7, v254, 29
	v_cvt_pk_bf16_f32 v18, v6, v7
	v_cvt_pk_bf16_f32 v19, v8, v9
	v_cvt_pk_bf16_f32 v20, v2, v3
	v_cvt_pk_bf16_f32 v21, v4, v5
	v_lshl_add_u64 v[22:23], s[6:7], 0, v[22:23]
	global_store_dwordx4 v[22:23], v[18:21], off sc1
.LBB0_1409:
	v_pk_mul_f32 v[14:15], v[14:15], v[14:15]
	v_pk_mul_f32 v[16:17], v[16:17], v[16:17]
	v_add_f32_e32 v14, v14, v15
	v_add_f32_e32 v14, v16, v14
	v_pk_mul_f32 v[10:11], v[10:11], v[10:11]
	v_add_f32_e32 v14, v17, v14
	v_add_f32_e32 v10, v10, v14
	v_pk_mul_f32 v[12:13], v[12:13], v[12:13]
	v_add_f32_e32 v10, v11, v10
	v_add_f32_e32 v10, v12, v10
	v_pk_mul_f32 v[6:7], v[6:7], v[6:7]
	v_add_f32_e32 v10, v13, v10
	v_add_f32_e32 v6, v6, v10
	v_pk_mul_f32 v[8:9], v[8:9], v[8:9]
	v_add_f32_e32 v6, v7, v6
	v_add_f32_e32 v6, v8, v6
	v_pk_mul_f32 v[2:3], v[2:3], v[2:3]
	v_add_f32_e32 v6, v9, v6
	v_add_f32_e32 v2, v2, v6
	v_pk_mul_f32 v[4:5], v[4:5], v[4:5]
	v_add_f32_e32 v2, v3, v2
	v_add_f32_e32 v2, v4, v2
	v_add_f32_e32 v2, v5, v2
	ds_bpermute_b32 v3, v120, v2
	s_waitcnt lgkmcnt(0)
	v_add_f32_e32 v2, v2, v3
	ds_bpermute_b32 v3, v121, v2
	s_and_saveexec_b64 s[6:7], s[0:1]
	s_cbranch_execz .LBB0_1411
	v_readlane_b32 s26, v254, 30
	v_lshlrev_b64 v[4:5], 6, v[94:95]
	v_readlane_b32 s27, v254, 31
	s_lshl_b32 s92, s39, 2
	s_waitcnt lgkmcnt(0)
	v_add_f32_e32 v2, v2, v3
	v_lshl_add_u64 v[4:5], s[26:27], 0, v[4:5]
	v_lshl_add_u64 v[4:5], s[24:25], 2, v[4:5]
	v_lshl_add_u64 v[4:5], v[4:5], 0, s[92:93]
	global_store_dword v[4:5], v2, off sc1

.LBB0_1449:
	v_lshl_add_u32 v188, s36, 8, v193
	v_ashrrev_i32_e32 v189, 31, v188
	v_lshlrev_b64 v[130:131], 6, v[188:189]
	v_or_b32_e32 v186, 16, v188
	v_lshl_add_u64 v[130:131], v[160:161], 0, v[130:131]
	v_ashrrev_i32_e32 v187, 31, v186
	global_load_dwordx4 v[200:203], v[130:131], off
	v_lshlrev_b64 v[130:131], 6, v[186:187]
	v_lshl_add_u64 v[130:131], v[160:161], 0, v[130:131]
	global_load_dwordx4 v[204:207], v[130:131], off
	v_or_b32_e32 v184, 32, v188
	v_ashrrev_i32_e32 v185, 31, v184
	v_lshlrev_b64 v[130:131], 6, v[184:185]
	v_or_b32_e32 v182, 48, v188
	v_lshl_add_u64 v[130:131], v[160:161], 0, v[130:131]
	v_ashrrev_i32_e32 v183, 31, v182
	global_load_dwordx4 v[150:153], v[130:131], off
	v_lshlrev_b64 v[130:131], 6, v[182:183]
	v_lshl_add_u64 v[130:131], v[160:161], 0, v[130:131]
	global_load_dwordx4 v[146:149], v[130:131], off
	v_add_u32_e32 v180, 0x80, v188
	v_ashrrev_i32_e32 v181, 31, v180
	v_lshlrev_b64 v[130:131], 6, v[180:181]
	v_add_u32_e32 v178, 0x90, v188
	v_lshl_add_u64 v[130:131], v[160:161], 0, v[130:131]
	v_ashrrev_i32_e32 v179, 31, v178
	global_load_dwordx4 v[142:145], v[130:131], off
	v_lshlrev_b64 v[130:131], 6, v[178:179]
	v_lshl_add_u64 v[130:131], v[160:161], 0, v[130:131]
	global_load_dwordx4 v[138:141], v[130:131], off
	v_add_u32_e32 v176, 0xa0, v188
	v_ashrrev_i32_e32 v177, 31, v176
	v_lshlrev_b64 v[130:131], 6, v[176:177]
	v_add_u32_e32 v174, 0xb0, v188
	v_lshl_add_u64 v[130:131], v[160:161], 0, v[130:131]
	v_ashrrev_i32_e32 v175, 31, v174
	global_load_dwordx4 v[134:137], v[130:131], off
	v_lshlrev_b64 v[130:131], 6, v[174:175]
	v_lshl_add_u64 v[130:131], v[160:161], 0, v[130:131]
	global_load_dwordx4 v[130:133], v[130:131], off
	v_and_b32_e32 v163, 64, v211
	v_xor_b32_e32 v162, 16, v211
	v_add_u32_e32 v163, 64, v163
	v_cmp_lt_i32_e32 vcc, v162, v163
	s_mov_b32 s4, 0x358637bd
	s_mov_b32 s16, 0x3a800000
	v_cndmask_b32_e32 v162, v211, v162, vcc
	v_lshlrev_b32_e32 v177, 2, v162
	v_xor_b32_e32 v162, 32, v211
	v_cmp_lt_i32_e32 vcc, v162, v163
	v_lshl_or_b32 v190, s35, 7, v198
	v_ashrrev_i32_e32 v191, 31, v190
	v_cndmask_b32_e32 v162, v211, v162, vcc
	v_lshlrev_b32_e32 v175, 2, v162
	s_movk_i32 s9, 0x1600
	s_waitcnt vmcnt(0)
	v_mov_b32_e32 v162, v201
	v_mov_b32_e32 v163, v202
	v_mov_b32_e32 v201, v203
	v_mov_b32_e32 v196, v205
	v_mov_b32_e32 v197, v206
	v_mov_b32_e32 v205, v207
	v_pk_add_f32 v[162:163], v[162:163], v[200:201]
	v_pk_add_f32 v[196:197], v[196:197], v[204:205]
	v_mov_b32_e32 v201, v162
	v_mov_b32_e32 v200, v196
	v_mov_b32_e32 v162, v197
	v_pk_add_f32 v[162:163], v[200:201], v[162:163]
	ds_bpermute_b32 v197, v177, v163
	ds_bpermute_b32 v196, v177, v162
	s_waitcnt lgkmcnt(0)
	v_pk_add_f32 v[162:163], v[162:163], v[196:197]
	ds_bpermute_b32 v197, v175, v163
	ds_bpermute_b32 v196, v175, v162
	s_waitcnt lgkmcnt(0)
	v_pk_add_f32 v[162:163], v[162:163], v[196:197]
	v_mov_b64_e32 v[196:197], s[4:5]
	v_pk_fma_f32 v[162:163], v[162:163], s[16:17], v[196:197] op_sel_hi:[1,0,0]
	s_nop 0
	v_mul_f32_e32 v164, 0x4b800000, v163
	v_cmp_gt_f32_e64 s[4:5], s91, v163
	v_cmp_gt_f32_e32 vcc, s91, v162
	s_nop 0
	v_cndmask_b32_e64 v163, v163, v164, s[4:5]
	v_rsq_f32_e32 v163, v163
	s_nop 0
	v_mul_f32_e32 v164, 0x45800000, v163
	v_cndmask_b32_e64 v194, v163, v164, s[4:5]
	v_mul_f32_e32 v163, 0x4b800000, v162
	v_cndmask_b32_e32 v162, v162, v163, vcc
	v_rsq_f32_e32 v162, v162
	v_pk_mul_f32 v[126:127], v[126:127], v[194:195] op_sel_hi:[1,0]
	v_pk_mul_f32 v[122:123], v[122:123], v[194:195] op_sel_hi:[1,0]
	v_pk_mul_f32 v[124:125], v[124:125], v[194:195] op_sel_hi:[1,0]
	v_mul_f32_e32 v163, 0x45800000, v162
	v_cndmask_b32_e32 v192, v162, v163, vcc
	v_mov_b32_e32 v162, v151
	v_mov_b32_e32 v163, v152
	v_mov_b32_e32 v151, v153
	v_mov_b32_e32 v152, v147
	v_mov_b32_e32 v153, v148
	v_mov_b32_e32 v147, v149
	v_pk_add_f32 v[150:151], v[162:163], v[150:151]
	v_pk_add_f32 v[146:147], v[152:153], v[146:147]
	v_mov_b32_e32 v149, v150
	v_mov_b32_e32 v148, v146
	v_mov_b32_e32 v150, v147
	v_pk_add_f32 v[146:147], v[148:149], v[150:151]
	ds_bpermute_b32 v149, v177, v147
	ds_bpermute_b32 v148, v177, v146
	v_mov_b32_e32 v150, v143
	v_mov_b32_e32 v151, v144
	v_mov_b32_e32 v143, v145
	v_mov_b32_e32 v144, v139
	v_mov_b32_e32 v145, v140
	v_mov_b32_e32 v139, v141
	v_pk_add_f32 v[142:143], v[150:151], v[142:143]
	v_pk_add_f32 v[138:139], v[144:145], v[138:139]
	s_waitcnt lgkmcnt(0)
	v_pk_add_f32 v[146:147], v[146:147], v[148:149]
	v_mov_b32_e32 v140, v138
	v_mov_b32_e32 v141, v142
	v_mov_b32_e32 v142, v139
	ds_bpermute_b32 v149, v175, v147
	ds_bpermute_b32 v148, v175, v146
	v_pk_add_f32 v[138:139], v[140:141], v[142:143]
	ds_bpermute_b32 v141, v177, v139
	ds_bpermute_b32 v140, v177, v138
	v_mov_b32_e32 v142, v135
	v_mov_b32_e32 v143, v136
	v_mov_b32_e32 v135, v137
	v_mov_b32_e32 v136, v131
	v_mov_b32_e32 v137, v132
	v_mov_b32_e32 v131, v133
	s_waitcnt lgkmcnt(2)
	v_pk_add_f32 v[146:147], v[146:147], v[148:149]
	v_pk_add_f32 v[134:135], v[142:143], v[134:135]
	v_pk_add_f32 v[130:131], v[136:137], v[130:131]
	v_pk_fma_f32 v[146:147], v[146:147], s[16:17], v[196:197] op_sel_hi:[1,0,0]
	s_waitcnt lgkmcnt(0)
	v_pk_add_f32 v[138:139], v[138:139], v[140:141]
	v_mov_b32_e32 v132, v130
	v_mov_b32_e32 v133, v134
	v_mov_b32_e32 v134, v131
	v_mul_f32_e32 v148, 0x4b800000, v147
	v_cmp_gt_f32_e64 s[4:5], s91, v147
	ds_bpermute_b32 v141, v175, v139
	ds_bpermute_b32 v140, v175, v138
	v_pk_add_f32 v[130:131], v[132:133], v[134:135]
	v_cndmask_b32_e64 v147, v147, v148, s[4:5]
	ds_bpermute_b32 v133, v177, v131
	ds_bpermute_b32 v132, v177, v130
	v_rsq_f32_e32 v147, v147
	s_waitcnt lgkmcnt(2)
	v_pk_add_f32 v[138:139], v[138:139], v[140:141]
	v_cmp_gt_f32_e32 vcc, s91, v146
	v_pk_fma_f32 v[138:139], v[138:139], s[16:17], v[196:197] op_sel_hi:[1,0,0]
	v_mul_f32_e32 v148, 0x45800000, v147
	s_waitcnt lgkmcnt(0)
	v_pk_add_f32 v[130:131], v[130:131], v[132:133]
	v_cndmask_b32_e64 v148, v147, v148, s[4:5]
	v_mul_f32_e32 v147, 0x4b800000, v146
	v_mul_f32_e32 v140, 0x4b800000, v139
	v_cmp_gt_f32_e64 s[4:5], s91, v139
	ds_bpermute_b32 v133, v175, v131
	ds_bpermute_b32 v132, v175, v130
	v_cndmask_b32_e32 v146, v146, v147, vcc
	v_cndmask_b32_e64 v139, v139, v140, s[4:5]
	v_rsq_f32_e32 v146, v146
	v_rsq_f32_e32 v139, v139
	s_waitcnt lgkmcnt(0)
	v_pk_add_f32 v[130:131], v[130:131], v[132:133]
	v_pk_mul_f32 v[118:119], v[118:119], v[194:195] op_sel_hi:[1,0]
	v_mul_f32_e32 v147, 0x45800000, v146
	v_mul_f32_e32 v140, 0x45800000, v139
	v_pk_fma_f32 v[130:131], v[130:131], s[16:17], v[196:197] op_sel_hi:[1,0,0]
	v_cndmask_b32_e32 v146, v146, v147, vcc
	v_cmp_gt_f32_e32 vcc, s91, v138
	v_cndmask_b32_e64 v140, v139, v140, s[4:5]
	v_mul_f32_e32 v139, 0x4b800000, v138
	v_mul_f32_e32 v132, 0x4b800000, v131
	v_cmp_gt_f32_e64 s[4:5], s91, v131
	v_cndmask_b32_e32 v138, v138, v139, vcc
	v_rsq_f32_e32 v138, v138
	v_cndmask_b32_e64 v131, v131, v132, s[4:5]
	v_rsq_f32_e32 v131, v131
	v_pk_mul_f32 v[114:115], v[114:115], v[194:195] op_sel_hi:[1,0]
	v_mul_f32_e32 v139, 0x45800000, v138
	v_cndmask_b32_e32 v138, v138, v139, vcc
	v_mul_f32_e32 v132, 0x45800000, v131
	v_cmp_gt_f32_e32 vcc, s91, v130
	v_cndmask_b32_e64 v132, v131, v132, s[4:5]
	v_mul_f32_e32 v131, 0x4b800000, v130
	v_cndmask_b32_e32 v130, v130, v131, vcc
	v_rsq_f32_e32 v130, v130
	v_readlane_b32 s4, v254, 32
	v_pk_mul_f32 v[116:117], v[116:117], v[194:195] op_sel_hi:[1,0]
	v_readlane_b32 s5, v254, 33
	v_mul_f32_e32 v131, 0x45800000, v130
	v_cndmask_b32_e32 v130, v130, v131, vcc
	v_mul_f32_e32 v131, 0xbfb8aa3b, v126
	v_exp_f32_e32 v131, v131
	v_pk_mul_f32 v[110:111], v[110:111], v[192:193] op_sel_hi:[1,0]
	v_pk_mul_f32 v[106:107], v[106:107], v[192:193] op_sel_hi:[1,0]
	v_pk_mul_f32 v[108:109], v[108:109], v[192:193] op_sel_hi:[1,0]
	v_add_f32_e32 v131, 1.0, v131
	v_rcp_f32_e32 v134, v131
	v_mul_f32_e32 v131, 0xbfb8aa3b, v127
	v_exp_f32_e32 v131, v131
	v_pk_mul_f32 v[102:103], v[102:103], v[192:193] op_sel_hi:[1,0]
	v_pk_mul_f32 v[98:99], v[98:99], v[192:193] op_sel_hi:[1,0]
	v_pk_mul_f32 v[100:101], v[100:101], v[192:193] op_sel_hi:[1,0]
	v_add_f32_e32 v131, 1.0, v131
	v_rcp_f32_e32 v135, v131
	v_pk_mul_f32 v[94:95], v[94:95], v[148:149] op_sel_hi:[1,0]
	v_pk_mul_f32 v[90:91], v[90:91], v[148:149] op_sel_hi:[1,0]
	v_pk_mul_f32 v[92:93], v[92:93], v[148:149] op_sel_hi:[1,0]
	v_pk_mul_f32 v[126:127], v[126:127], v[134:135]
	v_pk_mul_f32 v[86:87], v[86:87], v[148:149] op_sel_hi:[1,0]
	v_pk_mul_f32 v[122:123], v[122:123], v[126:127]
	v_pk_mul_f32 v[126:127], v[128:129], v[194:195] op_sel_hi:[1,0]
	v_pk_mul_f32 v[82:83], v[82:83], v[148:149] op_sel_hi:[1,0]
	v_mul_f32_e32 v128, 0xbfb8aa3b, v126
	v_mul_f32_e32 v129, 0xbfb8aa3b, v127
	v_exp_f32_e32 v128, v128
	v_exp_f32_e32 v129, v129
	v_pk_mul_f32 v[84:85], v[84:85], v[148:149] op_sel_hi:[1,0]
	v_pk_mul_f32 v[78:79], v[78:79], v[146:147] op_sel_hi:[1,0]
	v_add_f32_e32 v128, 1.0, v128
	v_add_f32_e32 v129, 1.0, v129
	v_rcp_f32_e32 v128, v128
	v_rcp_f32_e32 v129, v129
	v_pk_mul_f32 v[74:75], v[74:75], v[146:147] op_sel_hi:[1,0]
	v_pk_mul_f32 v[76:77], v[76:77], v[146:147] op_sel_hi:[1,0]
	v_pk_mul_f32 v[70:71], v[70:71], v[146:147] op_sel_hi:[1,0]
	v_pk_mul_f32 v[126:127], v[126:127], v[128:129]
	v_pk_mul_f32 v[66:67], v[66:67], v[146:147] op_sel_hi:[1,0]
	v_pk_mul_f32 v[124:125], v[124:125], v[126:127]
	v_mul_f32_e32 v126, 0xbfb8aa3b, v118
	v_mul_f32_e32 v127, 0xbfb8aa3b, v119
	v_exp_f32_e32 v126, v126
	v_exp_f32_e32 v127, v127
	v_pk_mul_f32 v[68:69], v[68:69], v[146:147] op_sel_hi:[1,0]
	v_pk_mul_f32 v[62:63], v[62:63], v[140:141] op_sel_hi:[1,0]
	v_add_f32_e32 v126, 1.0, v126
	v_add_f32_e32 v127, 1.0, v127
	v_rcp_f32_e32 v126, v126
	v_rcp_f32_e32 v127, v127
	v_pk_mul_f32 v[58:59], v[58:59], v[140:141] op_sel_hi:[1,0]
	v_pk_mul_f32 v[60:61], v[60:61], v[140:141] op_sel_hi:[1,0]
	v_pk_mul_f32 v[54:55], v[54:55], v[140:141] op_sel_hi:[1,0]
	v_pk_mul_f32 v[118:119], v[118:119], v[126:127]
	v_pk_mul_f32 v[50:51], v[50:51], v[140:141] op_sel_hi:[1,0]
	v_pk_mul_f32 v[114:115], v[114:115], v[118:119]
	v_pk_mul_f32 v[118:119], v[120:121], v[194:195] op_sel_hi:[1,0]
	v_pk_mul_f32 v[52:53], v[52:53], v[140:141] op_sel_hi:[1,0]
	v_mul_f32_e32 v120, 0xbfb8aa3b, v118
	v_mul_f32_e32 v121, 0xbfb8aa3b, v119
	v_exp_f32_e32 v120, v120
	v_exp_f32_e32 v121, v121
	v_pk_mul_f32 v[46:47], v[46:47], v[138:139] op_sel_hi:[1,0]
	v_pk_mul_f32 v[42:43], v[42:43], v[138:139] op_sel_hi:[1,0]
	v_add_f32_e32 v120, 1.0, v120
	v_add_f32_e32 v121, 1.0, v121
	v_rcp_f32_e32 v120, v120
	v_rcp_f32_e32 v121, v121
	v_pk_mul_f32 v[44:45], v[44:45], v[138:139] op_sel_hi:[1,0]
	v_pk_mul_f32 v[38:39], v[38:39], v[138:139] op_sel_hi:[1,0]
	v_pk_mul_f32 v[34:35], v[34:35], v[138:139] op_sel_hi:[1,0]
	v_pk_mul_f32 v[118:119], v[118:119], v[120:121]
	v_cvt_pk_bf16_f32 v120, v114, v115
	v_pk_mul_f32 v[116:117], v[116:117], v[118:119]
	v_mov_b64_e32 v[114:115], s[4:5]
	v_cvt_pk_bf16_f32 v118, v122, v123
	v_cvt_pk_bf16_f32 v121, v116, v117
	v_mad_i64_i32 v[122:123], s[4:5], v188, s9, v[114:115]
	v_lshlrev_b64 v[116:117], 1, v[190:191]
	v_cvt_pk_bf16_f32 v119, v124, v125
	v_lshl_add_u64 v[122:123], v[122:123], 0, v[116:117]
	global_store_dwordx4 v[122:123], v[118:121], off sc1
	v_pk_mul_f32 v[36:37], v[36:37], v[138:139] op_sel_hi:[1,0]
	v_pk_mul_f32 v[30:31], v[30:31], v[132:133] op_sel_hi:[1,0]
	v_mul_f32_e32 v118, 0xbfb8aa3b, v110
	v_mul_f32_e32 v119, 0xbfb8aa3b, v111
	v_exp_f32_e32 v118, v118
	v_exp_f32_e32 v119, v119
	v_pk_mul_f32 v[26:27], v[26:27], v[132:133] op_sel_hi:[1,0]
	v_pk_mul_f32 v[28:29], v[28:29], v[132:133] op_sel_hi:[1,0]
	v_add_f32_e32 v118, 1.0, v118
	v_add_f32_e32 v119, 1.0, v119
	v_rcp_f32_e32 v118, v118
	v_rcp_f32_e32 v119, v119
	v_pk_mul_f32 v[22:23], v[22:23], v[132:133] op_sel_hi:[1,0]
	v_pk_mul_f32 v[18:19], v[18:19], v[132:133] op_sel_hi:[1,0]
	v_pk_mul_f32 v[20:21], v[20:21], v[132:133] op_sel_hi:[1,0]
	v_pk_mul_f32 v[110:111], v[110:111], v[118:119]
	v_pk_mul_f32 v[14:15], v[14:15], v[130:131] op_sel_hi:[1,0]
	v_pk_mul_f32 v[106:107], v[106:107], v[110:111]
	v_pk_mul_f32 v[110:111], v[112:113], v[192:193] op_sel_hi:[1,0]
	v_pk_mul_f32 v[10:11], v[10:11], v[130:131] op_sel_hi:[1,0]
	v_mul_f32_e32 v112, 0xbfb8aa3b, v110
	v_mul_f32_e32 v113, 0xbfb8aa3b, v111
	v_exp_f32_e32 v112, v112
	v_exp_f32_e32 v113, v113
	v_pk_mul_f32 v[12:13], v[12:13], v[130:131] op_sel_hi:[1,0]
	v_pk_mul_f32 v[6:7], v[6:7], v[130:131] op_sel_hi:[1,0]
	v_add_f32_e32 v112, 1.0, v112
	v_add_f32_e32 v113, 1.0, v113
	v_rcp_f32_e32 v112, v112
	v_rcp_f32_e32 v113, v113
	v_pk_mul_f32 v[2:3], v[2:3], v[130:131] op_sel_hi:[1,0]
	v_pk_mul_f32 v[4:5], v[4:5], v[130:131] op_sel_hi:[1,0]
	s_andn2_b64 vcc, exec, s[0:1]
	v_pk_mul_f32 v[110:111], v[110:111], v[112:113]
	s_nop 0
	v_pk_mul_f32 v[108:109], v[108:109], v[110:111]
	v_mul_f32_e32 v110, 0xbfb8aa3b, v102
	v_mul_f32_e32 v111, 0xbfb8aa3b, v103
	v_exp_f32_e32 v110, v110
	v_exp_f32_e32 v111, v111
	v_add_f32_e32 v110, 1.0, v110
	v_add_f32_e32 v111, 1.0, v111
	v_rcp_f32_e32 v110, v110
	v_rcp_f32_e32 v111, v111
	s_nop 0
	v_pk_mul_f32 v[102:103], v[102:103], v[110:111]
	s_nop 0
	v_pk_mul_f32 v[102:103], v[98:99], v[102:103]
	v_pk_mul_f32 v[98:99], v[104:105], v[192:193] op_sel_hi:[1,0]
	s_nop 0
	v_mul_f32_e32 v104, 0xbfb8aa3b, v98
	v_mul_f32_e32 v105, 0xbfb8aa3b, v99
	v_exp_f32_e32 v104, v104
	v_exp_f32_e32 v105, v105
	v_add_f32_e32 v104, 1.0, v104
	v_add_f32_e32 v105, 1.0, v105
	v_rcp_f32_e32 v104, v104
	v_rcp_f32_e32 v105, v105
	s_nop 0
	v_pk_mul_f32 v[98:99], v[98:99], v[104:105]
	s_nop 0
	v_pk_mul_f32 v[104:105], v[100:101], v[98:99]
	v_cvt_pk_bf16_f32 v100, v102, v103
	v_mad_i64_i32 v[102:103], s[4:5], v186, s9, v[114:115]
	v_cvt_pk_bf16_f32 v98, v106, v107
	v_cvt_pk_bf16_f32 v99, v108, v109
	v_cvt_pk_bf16_f32 v101, v104, v105
	v_lshl_add_u64 v[102:103], v[102:103], 0, v[116:117]
	global_store_dwordx4 v[102:103], v[98:101], off sc1
	s_nop 1
	v_mul_f32_e32 v98, 0xbfb8aa3b, v94
	v_mul_f32_e32 v99, 0xbfb8aa3b, v95
	v_exp_f32_e32 v98, v98
	v_exp_f32_e32 v99, v99
	v_add_f32_e32 v98, 1.0, v98
	v_add_f32_e32 v99, 1.0, v99
	v_rcp_f32_e32 v98, v98
	v_rcp_f32_e32 v99, v99
	s_nop 0
	v_pk_mul_f32 v[94:95], v[94:95], v[98:99]
	s_nop 0
	v_pk_mul_f32 v[90:91], v[90:91], v[94:95]
	v_pk_mul_f32 v[94:95], v[96:97], v[148:149] op_sel_hi:[1,0]
	s_nop 0
	v_mul_f32_e32 v96, 0xbfb8aa3b, v94
	v_mul_f32_e32 v97, 0xbfb8aa3b, v95
	v_exp_f32_e32 v96, v96
	v_exp_f32_e32 v97, v97
	v_add_f32_e32 v96, 1.0, v96
	v_add_f32_e32 v97, 1.0, v97
	v_rcp_f32_e32 v96, v96
	v_rcp_f32_e32 v97, v97
	s_nop 0
	v_pk_mul_f32 v[94:95], v[94:95], v[96:97]
	s_nop 0
	v_pk_mul_f32 v[92:93], v[92:93], v[94:95]
	v_mul_f32_e32 v94, 0xbfb8aa3b, v86
	v_mul_f32_e32 v95, 0xbfb8aa3b, v87
	v_exp_f32_e32 v94, v94
	v_exp_f32_e32 v95, v95
	v_add_f32_e32 v94, 1.0, v94
	v_add_f32_e32 v95, 1.0, v95
	v_rcp_f32_e32 v94, v94
	v_rcp_f32_e32 v95, v95
	s_nop 0
	v_pk_mul_f32 v[86:87], v[86:87], v[94:95]
	s_nop 0
	v_pk_mul_f32 v[86:87], v[82:83], v[86:87]
	v_pk_mul_f32 v[82:83], v[88:89], v[148:149] op_sel_hi:[1,0]
	s_nop 0
	v_mul_f32_e32 v88, 0xbfb8aa3b, v82
	v_mul_f32_e32 v89, 0xbfb8aa3b, v83
	v_exp_f32_e32 v88, v88
	v_exp_f32_e32 v89, v89
	v_add_f32_e32 v88, 1.0, v88
	v_add_f32_e32 v89, 1.0, v89
	v_rcp_f32_e32 v88, v88
	v_rcp_f32_e32 v89, v89
	s_nop 0
	v_pk_mul_f32 v[82:83], v[82:83], v[88:89]
	s_nop 0
	v_pk_mul_f32 v[88:89], v[84:85], v[82:83]
	v_cvt_pk_bf16_f32 v84, v86, v87
	v_mad_i64_i32 v[86:87], s[4:5], v184, s9, v[114:115]
	v_cvt_pk_bf16_f32 v82, v90, v91
	v_cvt_pk_bf16_f32 v83, v92, v93
	v_cvt_pk_bf16_f32 v85, v88, v89
	v_lshl_add_u64 v[86:87], v[86:87], 0, v[116:117]
	global_store_dwordx4 v[86:87], v[82:85], off sc1
	s_nop 1
	v_mul_f32_e32 v82, 0xbfb8aa3b, v78
	v_mul_f32_e32 v83, 0xbfb8aa3b, v79
	v_exp_f32_e32 v82, v82
	v_exp_f32_e32 v83, v83
	v_add_f32_e32 v82, 1.0, v82
	v_add_f32_e32 v83, 1.0, v83
	v_rcp_f32_e32 v82, v82
	v_rcp_f32_e32 v83, v83
	s_nop 0
	v_pk_mul_f32 v[78:79], v[78:79], v[82:83]
	s_nop 0
	v_pk_mul_f32 v[74:75], v[74:75], v[78:79]
	v_pk_mul_f32 v[78:79], v[80:81], v[146:147] op_sel_hi:[1,0]
	s_nop 0
	v_mul_f32_e32 v80, 0xbfb8aa3b, v78
	v_mul_f32_e32 v81, 0xbfb8aa3b, v79
	v_exp_f32_e32 v80, v80
	v_exp_f32_e32 v81, v81
	v_add_f32_e32 v80, 1.0, v80
	v_add_f32_e32 v81, 1.0, v81
	v_rcp_f32_e32 v80, v80
	v_rcp_f32_e32 v81, v81
	s_nop 0
	v_pk_mul_f32 v[78:79], v[78:79], v[80:81]
	s_nop 0
	v_pk_mul_f32 v[76:77], v[76:77], v[78:79]
	v_mul_f32_e32 v78, 0xbfb8aa3b, v70
	v_mul_f32_e32 v79, 0xbfb8aa3b, v71
	v_exp_f32_e32 v78, v78
	v_exp_f32_e32 v79, v79
	v_add_f32_e32 v78, 1.0, v78
	v_add_f32_e32 v79, 1.0, v79
	v_rcp_f32_e32 v78, v78
	v_rcp_f32_e32 v79, v79
	s_nop 0
	v_pk_mul_f32 v[70:71], v[70:71], v[78:79]
	s_nop 0
	v_pk_mul_f32 v[70:71], v[66:67], v[70:71]
	v_pk_mul_f32 v[66:67], v[72:73], v[146:147] op_sel_hi:[1,0]
	s_nop 0
	v_mul_f32_e32 v72, 0xbfb8aa3b, v66
	v_mul_f32_e32 v73, 0xbfb8aa3b, v67
	v_exp_f32_e32 v72, v72
	v_exp_f32_e32 v73, v73
	v_add_f32_e32 v72, 1.0, v72
	v_add_f32_e32 v73, 1.0, v73
	v_rcp_f32_e32 v72, v72
	v_rcp_f32_e32 v73, v73
	s_nop 0
	v_pk_mul_f32 v[66:67], v[66:67], v[72:73]
	s_nop 0
	v_pk_mul_f32 v[72:73], v[68:69], v[66:67]
	v_cvt_pk_bf16_f32 v68, v70, v71
	v_mad_i64_i32 v[70:71], s[4:5], v182, s9, v[114:115]
	v_cvt_pk_bf16_f32 v66, v74, v75
	v_cvt_pk_bf16_f32 v67, v76, v77
	v_cvt_pk_bf16_f32 v69, v72, v73
	v_lshl_add_u64 v[70:71], v[70:71], 0, v[116:117]
	global_store_dwordx4 v[70:71], v[66:69], off sc1
	s_nop 1
	v_mul_f32_e32 v66, 0xbfb8aa3b, v62
	v_mul_f32_e32 v67, 0xbfb8aa3b, v63
	v_exp_f32_e32 v66, v66
	v_exp_f32_e32 v67, v67
	v_add_f32_e32 v66, 1.0, v66
	v_add_f32_e32 v67, 1.0, v67
	v_rcp_f32_e32 v66, v66
	v_rcp_f32_e32 v67, v67
	s_nop 0
	v_pk_mul_f32 v[62:63], v[62:63], v[66:67]
	s_nop 0
	v_pk_mul_f32 v[58:59], v[58:59], v[62:63]
	v_pk_mul_f32 v[62:63], v[64:65], v[140:141] op_sel_hi:[1,0]
	s_nop 0
	v_mul_f32_e32 v64, 0xbfb8aa3b, v62
	v_mul_f32_e32 v65, 0xbfb8aa3b, v63
	v_exp_f32_e32 v64, v64
	v_exp_f32_e32 v65, v65
	v_add_f32_e32 v64, 1.0, v64
	v_add_f32_e32 v65, 1.0, v65
	v_rcp_f32_e32 v64, v64
	v_rcp_f32_e32 v65, v65
	s_nop 0
	v_pk_mul_f32 v[62:63], v[62:63], v[64:65]
	s_nop 0
	v_pk_mul_f32 v[60:61], v[60:61], v[62:63]
	v_mul_f32_e32 v62, 0xbfb8aa3b, v54
	v_mul_f32_e32 v63, 0xbfb8aa3b, v55
	v_exp_f32_e32 v62, v62
	v_exp_f32_e32 v63, v63
	v_add_f32_e32 v62, 1.0, v62
	v_add_f32_e32 v63, 1.0, v63
	v_rcp_f32_e32 v62, v62
	v_rcp_f32_e32 v63, v63
	s_nop 0
	v_pk_mul_f32 v[54:55], v[54:55], v[62:63]
	s_nop 0
	v_pk_mul_f32 v[54:55], v[50:51], v[54:55]
	v_pk_mul_f32 v[50:51], v[56:57], v[140:141] op_sel_hi:[1,0]
	s_nop 0
	v_mul_f32_e32 v56, 0xbfb8aa3b, v50
	v_mul_f32_e32 v57, 0xbfb8aa3b, v51
	v_exp_f32_e32 v56, v56
	v_exp_f32_e32 v57, v57
	v_add_f32_e32 v56, 1.0, v56
	v_add_f32_e32 v57, 1.0, v57
	v_rcp_f32_e32 v56, v56
	v_rcp_f32_e32 v57, v57
	s_nop 0
	v_pk_mul_f32 v[50:51], v[50:51], v[56:57]
	s_nop 0
	v_pk_mul_f32 v[56:57], v[52:53], v[50:51]
	v_cvt_pk_bf16_f32 v52, v54, v55
	v_mad_i64_i32 v[54:55], s[4:5], v180, s9, v[114:115]
	v_cvt_pk_bf16_f32 v50, v58, v59
	v_cvt_pk_bf16_f32 v51, v60, v61
	v_cvt_pk_bf16_f32 v53, v56, v57
	v_lshl_add_u64 v[54:55], v[54:55], 0, v[116:117]
	global_store_dwordx4 v[54:55], v[50:53], off sc1
	s_nop 1
	v_mul_f32_e32 v50, 0xbfb8aa3b, v46
	v_mul_f32_e32 v51, 0xbfb8aa3b, v47
	v_exp_f32_e32 v50, v50
	v_exp_f32_e32 v51, v51
	v_add_f32_e32 v50, 1.0, v50
	v_add_f32_e32 v51, 1.0, v51
	v_rcp_f32_e32 v50, v50
	v_rcp_f32_e32 v51, v51
	s_nop 0
	v_pk_mul_f32 v[46:47], v[46:47], v[50:51]
	s_nop 0
	v_pk_mul_f32 v[42:43], v[42:43], v[46:47]
	v_pk_mul_f32 v[46:47], v[48:49], v[138:139] op_sel_hi:[1,0]
	s_nop 0
	v_mul_f32_e32 v48, 0xbfb8aa3b, v46
	v_mul_f32_e32 v49, 0xbfb8aa3b, v47
	v_exp_f32_e32 v48, v48
	v_exp_f32_e32 v49, v49
	v_add_f32_e32 v48, 1.0, v48
	v_add_f32_e32 v49, 1.0, v49
	v_rcp_f32_e32 v48, v48
	v_rcp_f32_e32 v49, v49
	s_nop 0
	v_pk_mul_f32 v[46:47], v[46:47], v[48:49]
	s_nop 0
	v_pk_mul_f32 v[44:45], v[44:45], v[46:47]
	v_mul_f32_e32 v46, 0xbfb8aa3b, v38
	v_mul_f32_e32 v47, 0xbfb8aa3b, v39
	v_exp_f32_e32 v46, v46
	v_exp_f32_e32 v47, v47
	v_add_f32_e32 v46, 1.0, v46
	v_add_f32_e32 v47, 1.0, v47
	v_rcp_f32_e32 v46, v46
	v_rcp_f32_e32 v47, v47
	s_nop 0
	v_pk_mul_f32 v[38:39], v[38:39], v[46:47]
	s_nop 0
	v_pk_mul_f32 v[38:39], v[34:35], v[38:39]
	v_pk_mul_f32 v[34:35], v[40:41], v[138:139] op_sel_hi:[1,0]
	s_nop 0
	v_mul_f32_e32 v40, 0xbfb8aa3b, v34
	v_mul_f32_e32 v41, 0xbfb8aa3b, v35
	v_exp_f32_e32 v40, v40
	v_exp_f32_e32 v41, v41
	v_add_f32_e32 v40, 1.0, v40
	v_add_f32_e32 v41, 1.0, v41
	v_rcp_f32_e32 v40, v40
	v_rcp_f32_e32 v41, v41
	s_nop 0
	v_pk_mul_f32 v[34:35], v[34:35], v[40:41]
	s_nop 0
	v_pk_mul_f32 v[40:41], v[36:37], v[34:35]
	v_cvt_pk_bf16_f32 v36, v38, v39
	v_mad_i64_i32 v[38:39], s[4:5], v178, s9, v[114:115]
	v_cvt_pk_bf16_f32 v34, v42, v43
	v_cvt_pk_bf16_f32 v35, v44, v45
	v_cvt_pk_bf16_f32 v37, v40, v41
	v_lshl_add_u64 v[38:39], v[38:39], 0, v[116:117]
	global_store_dwordx4 v[38:39], v[34:37], off sc1
	s_nop 1
	v_mul_f32_e32 v34, 0xbfb8aa3b, v30
	v_mul_f32_e32 v35, 0xbfb8aa3b, v31
	v_exp_f32_e32 v34, v34
	v_exp_f32_e32 v35, v35
	v_add_f32_e32 v34, 1.0, v34
	v_add_f32_e32 v35, 1.0, v35
	v_rcp_f32_e32 v34, v34
	v_rcp_f32_e32 v35, v35
	s_nop 0
	v_pk_mul_f32 v[30:31], v[30:31], v[34:35]
	s_nop 0
	v_pk_mul_f32 v[26:27], v[26:27], v[30:31]
	v_pk_mul_f32 v[30:31], v[32:33], v[132:133] op_sel_hi:[1,0]
	s_nop 0
	v_mul_f32_e32 v32, 0xbfb8aa3b, v30
	v_mul_f32_e32 v33, 0xbfb8aa3b, v31
	v_exp_f32_e32 v32, v32
	v_exp_f32_e32 v33, v33
	v_add_f32_e32 v32, 1.0, v32
	v_add_f32_e32 v33, 1.0, v33
	v_rcp_f32_e32 v32, v32
	v_rcp_f32_e32 v33, v33
	s_nop 0
	v_pk_mul_f32 v[30:31], v[30:31], v[32:33]
	s_nop 0
	v_pk_mul_f32 v[28:29], v[28:29], v[30:31]
	v_mul_f32_e32 v30, 0xbfb8aa3b, v22
	v_mul_f32_e32 v31, 0xbfb8aa3b, v23
	v_exp_f32_e32 v30, v30
	v_exp_f32_e32 v31, v31
	v_add_f32_e32 v30, 1.0, v30
	v_add_f32_e32 v31, 1.0, v31
	v_rcp_f32_e32 v30, v30
	v_rcp_f32_e32 v31, v31
	s_nop 0
	v_pk_mul_f32 v[22:23], v[22:23], v[30:31]
	s_nop 0
	v_pk_mul_f32 v[22:23], v[18:19], v[22:23]
	v_pk_mul_f32 v[18:19], v[24:25], v[132:133] op_sel_hi:[1,0]
	s_nop 0
	v_mul_f32_e32 v24, 0xbfb8aa3b, v18
	v_mul_f32_e32 v25, 0xbfb8aa3b, v19
	v_exp_f32_e32 v24, v24
	v_exp_f32_e32 v25, v25
	v_add_f32_e32 v24, 1.0, v24
	v_add_f32_e32 v25, 1.0, v25
	v_rcp_f32_e32 v24, v24
	v_rcp_f32_e32 v25, v25
	s_nop 0
	v_pk_mul_f32 v[18:19], v[18:19], v[24:25]
	s_nop 0
	v_pk_mul_f32 v[24:25], v[20:21], v[18:19]
	v_cvt_pk_bf16_f32 v20, v22, v23
	v_mad_i64_i32 v[22:23], s[4:5], v176, s9, v[114:115]
	v_cvt_pk_bf16_f32 v18, v26, v27
	v_cvt_pk_bf16_f32 v19, v28, v29
	v_cvt_pk_bf16_f32 v21, v24, v25
	v_lshl_add_u64 v[22:23], v[22:23], 0, v[116:117]
	global_store_dwordx4 v[22:23], v[18:21], off sc1
	s_nop 1
	v_mul_f32_e32 v18, 0xbfb8aa3b, v14
	v_mul_f32_e32 v19, 0xbfb8aa3b, v15
	v_exp_f32_e32 v18, v18
	v_exp_f32_e32 v19, v19
	v_add_f32_e32 v18, 1.0, v18
	v_add_f32_e32 v19, 1.0, v19
	v_rcp_f32_e32 v18, v18
	v_rcp_f32_e32 v19, v19
	s_nop 0
	v_pk_mul_f32 v[14:15], v[14:15], v[18:19]
	s_nop 0
	v_pk_mul_f32 v[10:11], v[10:11], v[14:15]
	v_pk_mul_f32 v[14:15], v[16:17], v[130:131] op_sel_hi:[1,0]
	s_nop 0
	v_mul_f32_e32 v16, 0xbfb8aa3b, v14
	v_mul_f32_e32 v17, 0xbfb8aa3b, v15
	v_exp_f32_e32 v16, v16
	v_exp_f32_e32 v17, v17
	v_add_f32_e32 v16, 1.0, v16
	v_add_f32_e32 v17, 1.0, v17
	v_rcp_f32_e32 v16, v16
	v_rcp_f32_e32 v17, v17
	s_nop 0
	v_pk_mul_f32 v[14:15], v[14:15], v[16:17]
	s_nop 0
	v_pk_mul_f32 v[12:13], v[12:13], v[14:15]
	v_mul_f32_e32 v14, 0xbfb8aa3b, v6
	v_mul_f32_e32 v15, 0xbfb8aa3b, v7
	v_exp_f32_e32 v14, v14
	v_exp_f32_e32 v15, v15
	v_add_f32_e32 v14, 1.0, v14
	v_add_f32_e32 v15, 1.0, v15
	v_rcp_f32_e32 v14, v14
	v_rcp_f32_e32 v15, v15
	s_nop 0
	v_pk_mul_f32 v[6:7], v[6:7], v[14:15]
	s_nop 0
	v_pk_mul_f32 v[6:7], v[2:3], v[6:7]
	v_pk_mul_f32 v[2:3], v[8:9], v[130:131] op_sel_hi:[1,0]
	s_nop 0
	v_mul_f32_e32 v8, 0xbfb8aa3b, v2
	v_mul_f32_e32 v9, 0xbfb8aa3b, v3
	v_exp_f32_e32 v8, v8
	v_exp_f32_e32 v9, v9
	v_add_f32_e32 v8, 1.0, v8
	v_add_f32_e32 v9, 1.0, v9
	v_rcp_f32_e32 v8, v8
	v_rcp_f32_e32 v9, v9
	s_nop 0
	v_pk_mul_f32 v[2:3], v[2:3], v[8:9]
	s_nop 0
	v_pk_mul_f32 v[8:9], v[4:5], v[2:3]
	v_cvt_pk_bf16_f32 v4, v6, v7
	v_mad_i64_i32 v[6:7], s[4:5], v174, s9, v[114:115]
	v_cvt_pk_bf16_f32 v2, v10, v11
	v_cvt_pk_bf16_f32 v3, v12, v13
	v_cvt_pk_bf16_f32 v5, v8, v9
	v_lshl_add_u64 v[6:7], v[6:7], 0, v[116:117]
	s_mov_b64 s[4:5], -1
	global_store_dwordx4 v[6:7], v[2:5], off sc1
	s_cbranch_vccnz .LBB0_1438
	s_andn2_b64 vcc, exec, s[2:3]
	s_cbranch_vccnz .LBB0_1437
	s_barrier
	s_branch .LBB0_1437
